# v5 + nt hint on phase 9 ACT stores and G row loads (keep unconsumed G tiles in the infinity cache) run 1
# baseline (speedup 1.0000x reference)
;     __device__ __forceinline__ void operator()(const f32x4 (&acc)[2][2][4][2], const Unit& u, int wr, int wc, int fr, int fq) const {
;     ...
;                 *(f32x4*)(w0 + e) = *(const f32x4*)(cw + col0 + e); *(f32x4*)(w1 + e) = *(const f32x4*)(cw + DFF + col0 + e);
;                 *(f32x4*)(w2 + e) = *(const f32x4*)(cw + 2 * DFF + col0 + e); *(f32x4*)(b + e) = *(const f32x4*)(cb + col0 + e); }
; #pragma unroll
;             for (int ai = 0; ai < 2; ++ai) {
; #pragma unroll
;               for (int mp = 0; mp < 4; mp += 2) {
;                 u32x4 g0[4], g1[4], g2[4]; float rs[4];
; #pragma unroll
;                 for (int m = mp; m < mp + 2; ++m) {
;                     const int row = row0 + ai * HALF + m * 16; const int tpos = row & (SEQ - 1);
;                     const bf16_t* gp = G + (size_t)row * DFF + col0;
;                     g2[m] = *(const u32x4*)gp;
;                     const bool edge = (ai == 0 && m == 0);
;                     g1[m] = *(const u32x4*)(gp - ((!edge || tpos >= 1) ? DFF : 0));
;                     g0[m] = *(const u32x4*)(gp - ((!edge || tpos >= 2) ? 2 * DFF : 0));
;                     rs[m] = ss[row];
;                 }
; #pragma unroll
;                 for (int m = mp; m < mp + 2; ++m) {
;                     const int row = row0 + ai * HALF + m * 16; const int tpos = row & (SEQ - 1);
;                     const u32x4 z4 = {0u, 0u, 0u, 0u};
;                     float f0[8], f1[8], f2[8], o[8];
;                     const bool edge = (ai == 0 && m == 0);
;                     unpack8((!edge || tpos >= 2) ? g0[m] : z4, f0); unpack8((!edge || tpos >= 1) ? g1[m] : z4, f1); unpack8(g2[m], f2);
;                     const float r = __builtin_amdgcn_rsqf(rs[m] * (1.f / DM) + EPS);
;                     const f32x4 v0 = acc[ai][bj][m][0] * r, v1 = acc[ai][bj][m][1] * r;
;                     const float uu[8] = {v0[0], v0[1], v0[2], v0[3], v1[0], v1[1], v1[2], v1[3]};
; #pragma unroll
;                     for (int e = 0; e < 8; ++e) { const float gc = b[e] + w0[e] * f0[e] + w1[e] * f1[e] + w2[e] * f2[e];
;                         const float sg = __builtin_amdgcn_rcpf(1.0f + __builtin_amdgcn_exp2f(-gc * 1.4426950408889634f));
;                         o[e] = gc * sg * uu[e]; }
.LBB0_1006:
	v_lshl_add_u32 v218, s6, 8, v223
	v_lshl_or_b32 v208, s7, 8, v225
	v_ashrrev_i32_e32 v209, 31, v208
	v_and_b32_e32 v182, 0x1fcf, v218
	v_lshlrev_b64 v[96:97], 2, v[208:209]
	v_lshl_add_u64 v[220:221], v[208:209], 1, s[18:19]
	v_cmp_eq_u32_e64 s[6:7], 0, v182
	v_lshl_add_u64 v[206:207], s[12:13], 0, v[96:97]
	v_lshl_add_u64 v[106:107], s[28:29], 0, v[96:97]
	v_lshl_add_u64 v[108:109], s[30:31], 0, v[96:97]
	v_mad_i64_i32 v[216:217], s[0:1], v218, s60, v[220:221]
	v_cndmask_b32_e64 v211, -1, 0, s[6:7]
	v_cndmask_b32_e64 v210, v230, 0, s[6:7]
	v_or_b32_e32 v214, 16, v218
	v_lshl_add_u64 v[204:205], s[14:15], 0, v[96:97]
	global_load_dwordx4 v[102:105], v[206:207], off offset:16
	global_load_dwordx4 v[114:117], v[206:207], off nt
	global_load_dwordx4 v[98:101], v[106:107], off offset:16
	global_load_dwordx4 v[110:113], v[106:107], off nt
	global_load_dwordx4 v[166:169], v[108:109], off offset:16
	global_load_dwordx4 v[174:177], v[108:109], off nt
	s_nop 0
	global_load_dwordx4 v[106:109], v[204:205], off offset:16
	global_load_dwordx4 v[118:121], v[204:205], off nt
	v_lshl_add_u64 v[96:97], v[210:211], 1, v[216:217]
	v_mad_i64_i32 v[158:159], s[0:1], v214, s60, v[220:221]
	global_load_dwordx4 v[178:181], v[96:97], off nt
	global_load_dwordx4 v[154:157], v[158:159], off nt
	v_add_co_u32_e32 v96, vcc, 0xffffe000, v158
	v_ashrrev_i32_e32 v219, 31, v218
	s_nop 0
	v_addc_co_u32_e32 v97, vcc, -1, v159, vcc
	v_add_co_u32_e32 v162, vcc, 0xffffb000, v158
	v_ashrrev_i32_e32 v215, 31, v214
	s_nop 0
	v_addc_co_u32_e32 v163, vcc, -1, v159, vcc
	v_lshl_add_u64 v[202:203], v[218:219], 2, s[22:23]
	global_load_dwordx4 v[158:161], v[96:97], off offset:-3072 nt
	s_nop 0
	global_load_dwordx4 v[162:165], v[162:163], off offset:-2048 nt
	v_lshl_add_u64 v[212:213], v[214:215], 2, s[22:23]
	global_load_dwordx4 v[170:173], v[216:217], off nt
	global_load_dword v219, v[202:203], off
	global_load_dword v97, v[212:213], off
	v_mov_b32_e32 v96, 0
	v_cmp_lt_u32_e64 s[8:9], 1, v182
	v_mov_b32_e32 v182, 0
	v_mov_b32_e32 v183, 0
	v_mov_b32_e32 v184, 0
	v_mov_b32_e32 v185, 0
	s_and_saveexec_b64 s[0:1], s[8:9]
	s_cbranch_execz .LBB0_1008
	v_add_co_u32_e32 v182, vcc, 0xffffb000, v216
	s_nop 1
	v_addc_co_u32_e32 v183, vcc, -1, v217, vcc
	global_load_dwordx4 v[182:185], v[182:183], off offset:-2048 nt
.LBB0_1008:
	s_or_b64 exec, exec, s[0:1]
	s_waitcnt vmcnt(0)
	v_cndmask_b32_e64 v236, v181, 0, s[6:7]
	v_fmamk_f32 v181, v219, 0x3a000000, v229
	v_cndmask_b32_e64 v238, v178, 0, s[6:7]
	v_lshlrev_b32_e32 v231, 16, v182
	v_and_b32_e32 v232, 0xffff0000, v182
	v_rsq_f32_e32 v182, v181
	v_cndmask_b32_e64 v219, v180, 0, s[6:7]
	v_cndmask_b32_e64 v237, v179, 0, s[6:7]
	v_lshlrev_b32_e32 v181, 16, v238
	v_lshlrev_b32_e32 v180, 16, v170
	v_mov_b32_e32 v178, v174
	v_mov_b32_e32 v179, v110
	v_fma_f32 v231, v114, v231, v118
	v_pk_mul_f32 v[180:181], v[178:179], v[180:181]
	v_fma_f32 v232, v115, v232, v119
	v_add_f32_e32 v110, v181, v231
	v_add_f32_e32 v231, v180, v110
	v_mul_f32_e32 v110, 0xbfb8aa3b, v231
	v_exp_f32_e32 v239, v110
	v_and_b32_e32 v181, 0xffff0000, v238
	v_and_b32_e32 v180, 0xffff0000, v170
	v_mov_b32_e32 v110, v175
	v_pk_mul_f32 v[174:175], v[110:111], v[180:181]
	v_lshlrev_b32_e32 v233, 16, v183
	v_add_f32_e32 v170, v175, v232
	v_add_f32_e32 v170, v174, v170
	v_mul_f32_e32 v174, 0xbfb8aa3b, v170
	v_exp_f32_e32 v174, v174
	v_add_f32_e32 v175, 1.0, v239
	v_rcp_f32_e32 v175, v175
	v_and_b32_e32 v183, 0xffff0000, v183
	v_add_f32_e32 v174, 1.0, v174
	v_rcp_f32_e32 v174, v174
	v_pk_mul_f32 v[150:151], v[150:151], v[182:183] op_sel_hi:[1,0]
	v_mul_f32_e32 v175, v231, v175
	v_pk_mul_f32 v[152:153], v[152:153], v[182:183] op_sel_hi:[1,0]
	v_pk_mul_f32 v[148:149], v[148:149], v[182:183] op_sel_hi:[1,0]
	v_pk_mul_f32 v[146:147], v[146:147], v[182:183] op_sel_hi:[1,0]
	v_mul_f32_e32 v182, v150, v175
	v_mul_f32_e32 v150, v170, v174
	v_lshlrev_b32_e32 v181, 16, v237
	v_lshlrev_b32_e32 v180, 16, v171
	v_mov_b32_e32 v174, v176
	v_mov_b32_e32 v175, v112
	v_fma_f32 v170, v116, v233, v120
	v_pk_mul_f32 v[180:181], v[174:175], v[180:181]
	v_fma_f32 v183, v117, v183, v121
	v_add_f32_e32 v112, v181, v170
	v_add_f32_e32 v176, v180, v112
	v_mul_f32_e32 v112, 0xbfb8aa3b, v176
	v_exp_f32_e32 v231, v112
	v_and_b32_e32 v181, 0xffff0000, v237
	v_and_b32_e32 v180, 0xffff0000, v171
	v_mov_b32_e32 v112, v177
	v_pk_mul_f32 v[170:171], v[112:113], v[180:181]
	v_mul_f32_e32 v180, v151, v150
	v_add_f32_e32 v171, v171, v183
	v_add_f32_e32 v177, v170, v171
	v_mul_f32_e32 v170, 0xbfb8aa3b, v177
	v_exp_f32_e32 v170, v170
	v_add_f32_e32 v150, 1.0, v231
	v_rcp_f32_e32 v181, v150
	v_lshlrev_b32_e32 v234, 16, v184
	v_add_f32_e32 v150, 1.0, v170
	v_rcp_f32_e32 v183, v150
	v_lshlrev_b32_e32 v151, 16, v219
	v_lshlrev_b32_e32 v150, 16, v172
	v_mov_b32_e32 v170, v166
	v_mov_b32_e32 v171, v98
	v_fma_f32 v231, v102, v234, v106
	v_pk_mul_f32 v[150:151], v[170:171], v[150:151]
	v_and_b32_e32 v184, 0xffff0000, v184
	v_add_f32_e32 v98, v151, v231
	v_add_f32_e32 v166, v150, v98
	v_mul_f32_e32 v98, 0xbfb8aa3b, v166
	v_exp_f32_e32 v98, v98
	v_mul_f32_e32 v150, v176, v181
	v_mul_f32_e32 v152, v152, v150
	v_mul_f32_e32 v176, v177, v183
	v_add_f32_e32 v98, 1.0, v98
	v_rcp_f32_e32 v177, v98
	v_and_b32_e32 v151, 0xffff0000, v219
	v_and_b32_e32 v150, 0xffff0000, v172
	v_mov_b32_e32 v98, v167
	v_fma_f32 v181, v103, v184, v107
	v_pk_mul_f32 v[150:151], v[98:99], v[150:151]
	v_lshlrev_b32_e32 v235, 16, v185
	v_add_f32_e32 v151, v151, v181
	v_add_f32_e32 v172, v150, v151
	v_mul_f32_e32 v150, 0xbfb8aa3b, v172
	v_exp_f32_e32 v150, v150
	v_mul_f32_e32 v151, v166, v177
	v_mul_f32_e32 v153, v153, v176
	v_mul_f32_e32 v146, v146, v151
; __device__ __forceinline__ unsigned cvt_pk_bf16(float lo, float hi) { unsigned r; asm volatile("v_cvt_pk_bf16_f32 %0, %1, %2" : "=v"(r) : "v"(lo), "v"(hi)); return r; }
;     __device__ __forceinline__ void operator()(const f32x4 (&acc)[2][2][4][2], const Unit& u, int wr, int wc, int fr, int fq) const {
;     ...
;                 for (int m = mp; m < mp + 2; ++m) {
;                     const int row = row0 + ai * HALF + m * 16; const int tpos = row & (SEQ - 1);
;                     const bf16_t* gp = G + (size_t)row * DFF + col0;
;                     g2[m] = *(const u32x4*)gp;
;                     const bool edge = (ai == 0 && m == 0);
;                     g1[m] = *(const u32x4*)(gp - ((!edge || tpos >= 1) ? DFF : 0));
;                     g0[m] = *(const u32x4*)(gp - ((!edge || tpos >= 2) ? 2 * DFF : 0));
;                     rs[m] = ss[row];
;     ...
;                 for (int m = mp; m < mp + 2; ++m) {
;                     const int row = row0 + ai * HALF + m * 16; const int tpos = row & (SEQ - 1);
;                     const u32x4 z4 = {0u, 0u, 0u, 0u};
;                     float f0[8], f1[8], f2[8], o[8];
;                     const bool edge = (ai == 0 && m == 0);
;                     unpack8((!edge || tpos >= 2) ? g0[m] : z4, f0); unpack8((!edge || tpos >= 1) ? g1[m] : z4, f1); unpack8(g2[m], f2);
;                     const float r = __builtin_amdgcn_rsqf(rs[m] * (1.f / DM) + EPS);
;                     const f32x4 v0 = acc[ai][bj][m][0] * r, v1 = acc[ai][bj][m][1] * r;
;                     const float uu[8] = {v0[0], v0[1], v0[2], v0[3], v1[0], v1[1], v1[2], v1[3]};
; #pragma unroll
;                     for (int e = 0; e < 8; ++e) { const float gc = b[e] + w0[e] * f0[e] + w1[e] * f1[e] + w2[e] * f2[e];
;                         const float sg = __builtin_amdgcn_rcpf(1.0f + __builtin_amdgcn_exp2f(-gc * 1.4426950408889634f));
;                         o[e] = gc * sg * uu[e]; }
;                     u32x4 w; w.x = cvt_pk_bf16(o[0], o[1]); w.y = cvt_pk_bf16(o[2], o[3]); w.z = cvt_pk_bf16(o[4], o[5]); w.w = cvt_pk_bf16(o[6], o[7]);
;                     *(u32x4*)(O + (size_t)row * DFF + col0) = w;
	v_add_f32_e32 v150, 1.0, v150
	v_rcp_f32_e32 v176, v150
	v_lshlrev_b32_e32 v151, 16, v236
	v_lshlrev_b32_e32 v150, 16, v173
	v_mov_b32_e32 v166, v168
	v_mov_b32_e32 v167, v100
	v_fma_f32 v177, v104, v235, v108
	v_pk_mul_f32 v[150:151], v[166:167], v[150:151]
	v_and_b32_e32 v185, 0xffff0000, v185
	v_add_f32_e32 v100, v151, v177
	v_add_f32_e32 v168, v150, v100
	v_mul_f32_e32 v100, 0xbfb8aa3b, v168
	v_exp_f32_e32 v177, v100
	v_and_b32_e32 v151, 0xffff0000, v236
	v_and_b32_e32 v150, 0xffff0000, v173
	v_mov_b32_e32 v100, v169
	v_fma_f32 v181, v105, v185, v109
	v_pk_mul_f32 v[150:151], v[100:101], v[150:151]
	v_mul_f32_e32 v169, v172, v176
	v_add_f32_e32 v151, v151, v181
	v_add_f32_e32 v150, v150, v151
	v_mul_f32_e32 v151, 0xbfb8aa3b, v150
	v_exp_f32_e32 v151, v151
	v_add_f32_e32 v172, 1.0, v177
	v_rcp_f32_e32 v172, v172
	v_mad_i64_i32 v[216:217], s[0:1], v218, s60, 0
	v_add_f32_e32 v151, 1.0, v151
	v_rcp_f32_e32 v151, v151
	v_mul_f32_e32 v168, v168, v172
	v_mul_f32_e32 v168, v148, v168
	v_mul_f32_e32 v147, v147, v169
	v_mul_f32_e32 v148, v150, v151
	v_mul_f32_e32 v151, v149, v148
	v_cvt_pk_bf16_f32 v148, v182, v180
	v_cvt_pk_bf16_f32 v149, v152, v153
	v_cvt_pk_bf16_f32 v150, v146, v147
	v_cvt_pk_bf16_f32 v151, v168, v151
	v_lshl_add_u64 v[146:147], s[20:21], 0, v[216:217]
	v_lshlrev_b64 v[168:169], 1, v[208:209]
	v_lshl_add_u64 v[146:147], v[146:147], 0, v[168:169]
	v_fmamk_f32 v97, v97, 0x3a000000, v229
	global_store_dwordx4 v[146:147], v[148:151], off nt
	v_and_b32_e32 v152, 0xffff0000, v162
	v_fma_f32 v152, v115, v152, v119
	v_rsq_f32_e32 v148, v97
	v_lshlrev_b32_e32 v149, 16, v162
	v_lshlrev_b32_e32 v151, 16, v158
	v_lshlrev_b32_e32 v150, 16, v154
	v_pk_mul_f32 v[144:145], v[144:145], v[148:149] op_sel_hi:[1,0]
	v_pk_mul_f32 v[142:143], v[142:143], v[148:149] op_sel_hi:[1,0]
	v_fma_f32 v149, v114, v149, v118
	v_pk_mul_f32 v[150:151], v[178:179], v[150:151]
	v_lshlrev_b32_e32 v153, 16, v163
	v_add_f32_e32 v149, v151, v149
	v_add_f32_e32 v149, v150, v149
	v_mul_f32_e32 v150, 0xbfb8aa3b, v149
	v_exp_f32_e32 v172, v150
	v_and_b32_e32 v151, 0xffff0000, v158
	v_and_b32_e32 v150, 0xffff0000, v154
	v_pk_mul_f32 v[150:151], v[110:111], v[150:151]
	v_pk_mul_f32 v[140:141], v[140:141], v[148:149] op_sel_hi:[1,0]
	v_add_f32_e32 v151, v151, v152
	v_add_f32_e32 v150, v150, v151
	v_mul_f32_e32 v151, 0xbfb8aa3b, v150
	v_exp_f32_e32 v151, v151
	v_add_f32_e32 v152, 1.0, v172
	v_rcp_f32_e32 v152, v152
	v_pk_mul_f32 v[138:139], v[138:139], v[148:149] op_sel_hi:[1,0]
	v_add_f32_e32 v151, 1.0, v151
	v_rcp_f32_e32 v151, v151
	v_mul_f32_e32 v148, v149, v152
	v_mul_f32_e32 v152, v142, v148
	v_lshlrev_b32_e32 v149, 16, v159
	v_lshlrev_b32_e32 v148, 16, v155
	v_mul_f32_e32 v142, v150, v151
	v_fma_f32 v150, v116, v153, v120
	v_pk_mul_f32 v[148:149], v[174:175], v[148:149]
	v_and_b32_e32 v162, 0xffff0000, v163
	v_add_f32_e32 v149, v149, v150
	v_add_f32_e32 v150, v148, v149
	v_mul_f32_e32 v148, 0xbfb8aa3b, v150
	v_exp_f32_e32 v151, v148
	v_and_b32_e32 v149, 0xffff0000, v159
	v_and_b32_e32 v148, 0xffff0000, v155
	v_fma_f32 v153, v117, v162, v121
	v_pk_mul_f32 v[148:149], v[112:113], v[148:149]
	v_lshlrev_b32_e32 v163, 16, v164
	v_add_f32_e32 v149, v149, v153
	v_add_f32_e32 v148, v148, v149
	v_mul_f32_e32 v149, 0xbfb8aa3b, v148
	v_exp_f32_e32 v149, v149
	v_mul_f32_e32 v153, v143, v142
	v_add_f32_e32 v142, 1.0, v151
	v_rcp_f32_e32 v151, v142
	v_add_f32_e32 v142, 1.0, v149
	v_rcp_f32_e32 v149, v142
	v_lshlrev_b32_e32 v143, 16, v160
	v_lshlrev_b32_e32 v142, 16, v156
	v_fma_f32 v154, v102, v163, v106
	v_pk_mul_f32 v[142:143], v[170:171], v[142:143]
	v_and_b32_e32 v97, 0xffff0000, v164
	v_add_f32_e32 v143, v143, v154
	v_add_f32_e32 v154, v142, v143
	v_mul_f32_e32 v142, 0xbfb8aa3b, v154
	v_exp_f32_e32 v142, v142
	v_mul_f32_e32 v143, v150, v151
	v_mul_f32_e32 v144, v144, v143
	v_mul_f32_e32 v148, v148, v149
	v_add_f32_e32 v142, 1.0, v142
	v_rcp_f32_e32 v149, v142
	v_and_b32_e32 v143, 0xffff0000, v160
	v_and_b32_e32 v142, 0xffff0000, v156
	v_fma_f32 v97, v103, v97, v107
	v_pk_mul_f32 v[142:143], v[98:99], v[142:143]
	v_lshlrev_b32_e32 v164, 16, v165
	v_add_f32_e32 v97, v143, v97
	v_add_f32_e32 v97, v142, v97
	v_mul_f32_e32 v142, 0xbfb8aa3b, v97
	v_exp_f32_e32 v142, v142
	v_mul_f32_e32 v143, v154, v149
	v_mul_f32_e32 v145, v145, v148
	v_mul_f32_e32 v148, v138, v143
	v_add_f32_e32 v138, 1.0, v142
	v_lshlrev_b32_e32 v143, 16, v161
	v_lshlrev_b32_e32 v142, 16, v157
	v_fma_f32 v149, v104, v164, v108
	v_pk_mul_f32 v[142:143], v[166:167], v[142:143]
	v_and_b32_e32 v165, 0xffff0000, v165
	v_add_f32_e32 v143, v143, v149
	v_add_f32_e32 v149, v142, v143
	v_mul_f32_e32 v142, 0xbfb8aa3b, v149
	v_exp_f32_e32 v150, v142
	v_and_b32_e32 v143, 0xffff0000, v161
	v_and_b32_e32 v142, 0xffff0000, v157
	v_fma_f32 v151, v105, v165, v109
	v_pk_mul_f32 v[142:143], v[100:101], v[142:143]
	v_rcp_f32_e32 v138, v138
	v_add_f32_e32 v143, v143, v151
	v_add_f32_e32 v142, v142, v143
	v_mul_f32_e32 v143, 0xbfb8aa3b, v142
	v_exp_f32_e32 v143, v143
	v_mul_f32_e32 v97, v97, v138
	v_add_f32_e32 v138, 1.0, v150
	v_rcp_f32_e32 v138, v138
	v_add_f32_e32 v143, 1.0, v143
	v_rcp_f32_e32 v143, v143
	v_mad_i64_i32 v[214:215], s[0:1], v214, s60, 0
	v_mul_f32_e32 v138, v149, v138
	v_mul_f32_e32 v149, v140, v138
	v_mul_f32_e32 v138, v142, v143
	v_mul_f32_e32 v141, v141, v138
	v_lshl_add_u64 v[142:143], s[20:21], 0, v[214:215]
	v_mul_f32_e32 v97, v139, v97
	v_cvt_pk_bf16_f32 v138, v152, v153
	v_cvt_pk_bf16_f32 v139, v144, v145
	v_cvt_pk_bf16_f32 v140, v148, v97
	v_cvt_pk_bf16_f32 v141, v149, v141
	v_lshl_add_u64 v[148:149], v[142:143], 0, v[168:169]
	v_or_b32_e32 v156, 32, v218
	global_store_dwordx4 v[148:149], v[138:141], off nt
	v_ashrrev_i32_e32 v157, 31, v156
	v_lshl_add_u64 v[150:151], v[156:157], 2, s[22:23]
	v_mad_i64_i32 v[138:139], s[0:1], v156, s60, v[220:221]
	v_add_co_u32_e32 v140, vcc, s62, v138
	global_load_dword v97, v[150:151], off
	s_nop 0
	v_addc_co_u32_e32 v141, vcc, -1, v139, vcc
	global_load_dwordx4 v[158:161], v[140:141], off offset:-2048 nt
	v_add_co_u32_e32 v140, vcc, s61, v138
	v_or_b32_e32 v152, 48, v218
	s_nop 0
	v_addc_co_u32_e32 v141, vcc, -1, v139, vcc
	global_load_dwordx4 v[162:165], v[140:141], off offset:-3072 nt
	global_load_dwordx4 v[180:183], v[138:139], off nt
	v_mad_i64_i32 v[154:155], s[0:1], v152, s60, v[220:221]
	v_add_co_u32_e32 v142, vcc, s61, v154
	v_ashrrev_i32_e32 v153, 31, v152
	s_nop 0
	v_addc_co_u32_e32 v143, vcc, -1, v155, vcc
	global_load_dwordx4 v[138:141], v[154:155], off nt
	s_nop 0
	global_load_dwordx4 v[142:145], v[142:143], off offset:-3072 nt
	v_add_co_u32_e32 v154, vcc, s62, v154
	s_waitcnt vmcnt(5)
; __device__ __forceinline__ unsigned cvt_pk_bf16(float lo, float hi) { unsigned r; asm volatile("v_cvt_pk_bf16_f32 %0, %1, %2" : "=v"(r) : "v"(lo), "v"(hi)); return r; }
;     __device__ __forceinline__ void operator()(const f32x4 (&acc)[2][2][4][2], const Unit& u, int wr, int wc, int fr, int fq) const {
;     ...
;                 for (int m = mp; m < mp + 2; ++m) {
;                     const int row = row0 + ai * HALF + m * 16; const int tpos = row & (SEQ - 1);
;                     const bf16_t* gp = G + (size_t)row * DFF + col0;
;                     g2[m] = *(const u32x4*)gp;
;                     const bool edge = (ai == 0 && m == 0);
;                     g1[m] = *(const u32x4*)(gp - ((!edge || tpos >= 1) ? DFF : 0));
;                     g0[m] = *(const u32x4*)(gp - ((!edge || tpos >= 2) ? 2 * DFF : 0));
;                     rs[m] = ss[row];
;                 }
; #pragma unroll
;                 for (int m = mp; m < mp + 2; ++m) {
;                     const int row = row0 + ai * HALF + m * 16; const int tpos = row & (SEQ - 1);
;                     const u32x4 z4 = {0u, 0u, 0u, 0u};
;                     float f0[8], f1[8], f2[8], o[8];
;                     const bool edge = (ai == 0 && m == 0);
;                     unpack8((!edge || tpos >= 2) ? g0[m] : z4, f0); unpack8((!edge || tpos >= 1) ? g1[m] : z4, f1); unpack8(g2[m], f2);
;                     const float r = __builtin_amdgcn_rsqf(rs[m] * (1.f / DM) + EPS);
;                     const f32x4 v0 = acc[ai][bj][m][0] * r, v1 = acc[ai][bj][m][1] * r;
;                     const float uu[8] = {v0[0], v0[1], v0[2], v0[3], v1[0], v1[1], v1[2], v1[3]};
; #pragma unroll
;                     for (int e = 0; e < 8; ++e) { const float gc = b[e] + w0[e] * f0[e] + w1[e] * f1[e] + w2[e] * f2[e];
;                         const float sg = __builtin_amdgcn_rcpf(1.0f + __builtin_amdgcn_exp2f(-gc * 1.4426950408889634f));
;                         o[e] = gc * sg * uu[e]; }
;                     u32x4 w; w.x = cvt_pk_bf16(o[0], o[1]); w.y = cvt_pk_bf16(o[2], o[3]); w.z = cvt_pk_bf16(o[4], o[5]); w.w = cvt_pk_bf16(o[6], o[7]);
;                     *(u32x4*)(O + (size_t)row * DFF + col0) = w;
;                 }
	v_fmamk_f32 v97, v97, 0x3a000000, v229
	v_addc_co_u32_e32 v155, vcc, -1, v155, vcc
	global_load_dwordx4 v[232:235], v[154:155], off offset:-2048 nt
	v_lshl_add_u64 v[154:155], v[152:153], 2, s[22:23]
	global_load_dword v153, v[154:155], off
	s_waitcnt vmcnt(6)
	v_lshlrev_b32_e32 v157, 16, v158
	v_and_b32_e32 v172, 0xffff0000, v158
	v_lshlrev_b32_e32 v177, 16, v160
	v_rsq_f32_e32 v158, v97
	v_and_b32_e32 v97, 0xffff0000, v160
	v_lshlrev_b32_e32 v184, 16, v161
	v_and_b32_e32 v185, 0xffff0000, v161
	s_waitcnt vmcnt(5)
	v_lshlrev_b32_e32 v161, 16, v162
	s_waitcnt vmcnt(4)
	v_lshlrev_b32_e32 v160, 16, v180
	v_fma_f32 v157, v114, v157, v118
	v_pk_mul_f32 v[160:161], v[178:179], v[160:161]
	v_fma_f32 v172, v115, v172, v119
	v_add_f32_e32 v157, v161, v157
	v_add_f32_e32 v157, v160, v157
	v_and_b32_e32 v161, 0xffff0000, v162
	v_and_b32_e32 v160, 0xffff0000, v180
	v_pk_mul_f32 v[160:161], v[110:111], v[160:161]
	v_lshlrev_b32_e32 v173, 16, v159
	v_add_f32_e32 v161, v161, v172
	v_and_b32_e32 v176, 0xffff0000, v159
	v_pk_mul_f32 v[136:137], v[136:137], v[158:159] op_sel_hi:[1,0]
	v_pk_mul_f32 v[134:135], v[134:135], v[158:159] op_sel_hi:[1,0]
	v_mul_f32_e32 v159, 0xbfb8aa3b, v157
	v_add_f32_e32 v160, v160, v161
	v_exp_f32_e32 v159, v159
	v_mul_f32_e32 v161, 0xbfb8aa3b, v160
	v_exp_f32_e32 v161, v161
	v_fma_f32 v162, v117, v176, v121
	v_pk_mul_f32 v[132:133], v[132:133], v[158:159] op_sel_hi:[1,0]
	v_add_f32_e32 v159, 1.0, v159
	v_rcp_f32_e32 v159, v159
	v_add_f32_e32 v161, 1.0, v161
	v_rcp_f32_e32 v161, v161
	v_fma_f32 v97, v103, v97, v107
	v_pk_mul_f32 v[130:131], v[130:131], v[158:159] op_sel_hi:[1,0]
	v_mul_f32_e32 v157, v157, v159
	v_lshlrev_b32_e32 v159, 16, v163
	v_lshlrev_b32_e32 v158, 16, v181
	v_mul_f32_e32 v157, v134, v157
	v_mul_f32_e32 v134, v160, v161
	v_fma_f32 v160, v116, v173, v120
	v_pk_mul_f32 v[158:159], v[174:175], v[158:159]
	s_nop 0
	v_add_f32_e32 v159, v159, v160
	v_add_f32_e32 v160, v158, v159
	v_mul_f32_e32 v158, 0xbfb8aa3b, v160
	v_exp_f32_e32 v161, v158
	v_and_b32_e32 v159, 0xffff0000, v163
	v_and_b32_e32 v158, 0xffff0000, v181
	v_pk_mul_f32 v[158:159], v[112:113], v[158:159]
	v_fma_f32 v163, v102, v177, v106
	v_add_f32_e32 v159, v159, v162
	v_add_f32_e32 v158, v158, v159
	v_mul_f32_e32 v159, 0xbfb8aa3b, v158
	v_exp_f32_e32 v159, v159
	v_mul_f32_e32 v162, v135, v134
	v_add_f32_e32 v134, 1.0, v161
	v_rcp_f32_e32 v161, v134
	v_add_f32_e32 v134, 1.0, v159
	v_rcp_f32_e32 v159, v134
	v_lshlrev_b32_e32 v135, 16, v164
	v_lshlrev_b32_e32 v134, 16, v182
	v_pk_mul_f32 v[134:135], v[170:171], v[134:135]
	v_mul_f32_e32 v158, v158, v159
	v_add_f32_e32 v135, v135, v163
	v_add_f32_e32 v163, v134, v135
	v_mul_f32_e32 v134, 0xbfb8aa3b, v163
	v_exp_f32_e32 v134, v134
	v_mul_f32_e32 v135, v160, v161
	v_mul_f32_e32 v136, v136, v135
	v_and_b32_e32 v135, 0xffff0000, v164
	v_add_f32_e32 v134, 1.0, v134
	v_rcp_f32_e32 v159, v134
	v_and_b32_e32 v134, 0xffff0000, v182
	v_pk_mul_f32 v[134:135], v[98:99], v[134:135]
	v_mul_f32_e32 v137, v137, v158
	v_add_f32_e32 v97, v135, v97
	v_add_f32_e32 v97, v134, v97
	v_mul_f32_e32 v134, 0xbfb8aa3b, v97
	v_exp_f32_e32 v134, v134
	v_mul_f32_e32 v135, v163, v159
	v_mul_f32_e32 v130, v130, v135
	v_lshlrev_b32_e32 v135, 16, v165
	v_add_f32_e32 v134, 1.0, v134
	v_rcp_f32_e32 v158, v134
	v_lshlrev_b32_e32 v134, 16, v183
	v_fma_f32 v159, v104, v184, v108
	v_pk_mul_f32 v[134:135], v[166:167], v[134:135]
	v_fma_f32 v161, v105, v185, v109
	v_add_f32_e32 v135, v135, v159
	v_add_f32_e32 v159, v134, v135
	v_mul_f32_e32 v134, 0xbfb8aa3b, v159
	v_exp_f32_e32 v160, v134
	v_and_b32_e32 v135, 0xffff0000, v165
	v_and_b32_e32 v134, 0xffff0000, v183
	v_pk_mul_f32 v[134:135], v[100:101], v[134:135]
	v_mul_f32_e32 v97, v97, v158
	v_add_f32_e32 v135, v135, v161
	v_add_f32_e32 v134, v134, v135
	v_mul_f32_e32 v135, 0xbfb8aa3b, v134
	v_exp_f32_e32 v135, v135
	v_add_f32_e32 v158, 1.0, v160
	v_rcp_f32_e32 v158, v158
	v_mul_f32_e32 v97, v131, v97
	v_add_f32_e32 v135, 1.0, v135
	v_rcp_f32_e32 v135, v135
	v_mul_f32_e32 v131, v159, v158
	v_mul_f32_e32 v131, v132, v131
	s_waitcnt vmcnt(1)
	v_and_b32_e32 v158, 0xffff0000, v233
	v_mul_f32_e32 v132, v134, v135
	v_mul_f32_e32 v135, v133, v132
	v_cvt_pk_bf16_f32 v132, v157, v162
	v_cvt_pk_bf16_f32 v133, v136, v137
	v_mov_b64_e32 v[136:137], s[20:21]
	v_cvt_pk_bf16_f32 v134, v130, v97
	v_cvt_pk_bf16_f32 v135, v131, v135
	v_mad_i64_i32 v[130:131], s[0:1], v156, s60, v[136:137]
	v_lshl_add_u64 v[130:131], v[130:131], 0, v[168:169]
	global_store_dwordx4 v[130:131], v[132:135], off nt
	v_lshlrev_b32_e32 v97, 16, v232
	v_fma_f32 v97, v114, v97, v118
	v_lshlrev_b32_e32 v135, 16, v142
	v_lshlrev_b32_e32 v134, 16, v138
	s_waitcnt vmcnt(1)
; __device__ __forceinline__ unsigned cvt_pk_bf16(float lo, float hi) { unsigned r; asm volatile("v_cvt_pk_bf16_f32 %0, %1, %2" : "=v"(r) : "v"(lo), "v"(hi)); return r; }
;     __device__ __forceinline__ void operator()(const f32x4 (&acc)[2][2][4][2], const Unit& u, int wr, int wc, int fr, int fq) const {
;     ...
;                 for (int m = mp; m < mp + 2; ++m) {
;                     const int row = row0 + ai * HALF + m * 16; const int tpos = row & (SEQ - 1);
;                     const bf16_t* gp = G + (size_t)row * DFF + col0;
;                     g2[m] = *(const u32x4*)gp;
;                     const bool edge = (ai == 0 && m == 0);
;                     g1[m] = *(const u32x4*)(gp - ((!edge || tpos >= 1) ? DFF : 0));
;                     g0[m] = *(const u32x4*)(gp - ((!edge || tpos >= 2) ? 2 * DFF : 0));
;                     rs[m] = ss[row];
;                 }
; #pragma unroll
;                 for (int m = mp; m < mp + 2; ++m) {
;                     const int row = row0 + ai * HALF + m * 16; const int tpos = row & (SEQ - 1);
;                     const u32x4 z4 = {0u, 0u, 0u, 0u};
;                     float f0[8], f1[8], f2[8], o[8];
;                     const bool edge = (ai == 0 && m == 0);
;                     unpack8((!edge || tpos >= 2) ? g0[m] : z4, f0); unpack8((!edge || tpos >= 1) ? g1[m] : z4, f1); unpack8(g2[m], f2);
;                     const float r = __builtin_amdgcn_rsqf(rs[m] * (1.f / DM) + EPS);
;                     const f32x4 v0 = acc[ai][bj][m][0] * r, v1 = acc[ai][bj][m][1] * r;
;                     const float uu[8] = {v0[0], v0[1], v0[2], v0[3], v1[0], v1[1], v1[2], v1[3]};
; #pragma unroll
;                     for (int e = 0; e < 8; ++e) { const float gc = b[e] + w0[e] * f0[e] + w1[e] * f1[e] + w2[e] * f2[e];
;                         const float sg = __builtin_amdgcn_rcpf(1.0f + __builtin_amdgcn_exp2f(-gc * 1.4426950408889634f));
;                         o[e] = gc * sg * uu[e]; }
;                     u32x4 w; w.x = cvt_pk_bf16(o[0], o[1]); w.y = cvt_pk_bf16(o[2], o[3]); w.z = cvt_pk_bf16(o[4], o[5]); w.w = cvt_pk_bf16(o[6], o[7]);
;                     *(u32x4*)(O + (size_t)row * DFF + col0) = w;
;                 }
	v_fmamk_f32 v132, v153, 0x3a000000, v229
	v_pk_mul_f32 v[134:135], v[178:179], v[134:135]
	v_rsq_f32_e32 v132, v132
	v_add_f32_e32 v97, v135, v97
	v_add_f32_e32 v97, v134, v97
	v_mul_f32_e32 v134, 0xbfb8aa3b, v97
	v_and_b32_e32 v133, 0xffff0000, v232
	v_exp_f32_e32 v162, v134
	v_and_b32_e32 v135, 0xffff0000, v142
	v_and_b32_e32 v134, 0xffff0000, v138
	v_pk_mul_f32 v[128:129], v[128:129], v[132:133] op_sel_hi:[1,0]
	v_pk_mul_f32 v[126:127], v[126:127], v[132:133] op_sel_hi:[1,0]
	v_fma_f32 v133, v115, v133, v119
	v_pk_mul_f32 v[134:135], v[110:111], v[134:135]
	v_lshlrev_b32_e32 v157, 16, v233
	v_add_f32_e32 v133, v135, v133
	v_add_f32_e32 v133, v134, v133
	v_mul_f32_e32 v134, 0xbfb8aa3b, v133
	v_exp_f32_e32 v134, v134
	v_add_f32_e32 v135, 1.0, v162
	v_rcp_f32_e32 v135, v135
	v_pk_mul_f32 v[124:125], v[124:125], v[132:133] op_sel_hi:[1,0]
	v_add_f32_e32 v134, 1.0, v134
	v_rcp_f32_e32 v134, v134
	v_mul_f32_e32 v97, v97, v135
	v_pk_mul_f32 v[122:123], v[122:123], v[132:133] op_sel_hi:[1,0]
	v_mul_f32_e32 v97, v126, v97
	v_mul_f32_e32 v126, v133, v134
	v_lshlrev_b32_e32 v133, 16, v143
	v_lshlrev_b32_e32 v132, 16, v139
	v_fma_f32 v134, v116, v157, v120
	v_pk_mul_f32 v[132:133], v[174:175], v[132:133]
	v_fma_f32 v138, v117, v158, v121
	v_add_f32_e32 v133, v133, v134
	v_add_f32_e32 v134, v132, v133
	v_mul_f32_e32 v132, 0xbfb8aa3b, v134
	v_exp_f32_e32 v135, v132
	v_and_b32_e32 v133, 0xffff0000, v143
	v_and_b32_e32 v132, 0xffff0000, v139
	v_pk_mul_f32 v[132:133], v[112:113], v[132:133]
	v_lshlrev_b32_e32 v159, 16, v234
	v_add_f32_e32 v133, v133, v138
	v_add_f32_e32 v132, v132, v133
	v_mul_f32_e32 v133, 0xbfb8aa3b, v132
	v_exp_f32_e32 v133, v133
	v_mul_f32_e32 v138, v127, v126
	v_add_f32_e32 v126, 1.0, v135
	v_rcp_f32_e32 v135, v126
	v_add_f32_e32 v126, 1.0, v133
	v_rcp_f32_e32 v133, v126
	v_lshlrev_b32_e32 v127, 16, v144
	v_lshlrev_b32_e32 v126, 16, v140
	v_fma_f32 v139, v102, v159, v106
	v_pk_mul_f32 v[126:127], v[170:171], v[126:127]
	v_and_b32_e32 v153, 0xffff0000, v234
	v_add_f32_e32 v127, v127, v139
	v_add_f32_e32 v139, v126, v127
	v_mul_f32_e32 v126, 0xbfb8aa3b, v139
	v_exp_f32_e32 v126, v126
	v_mul_f32_e32 v127, v134, v135
	v_mul_f32_e32 v128, v128, v127
	v_mul_f32_e32 v132, v132, v133
	v_add_f32_e32 v126, 1.0, v126
	v_rcp_f32_e32 v133, v126
	v_and_b32_e32 v127, 0xffff0000, v144
	v_and_b32_e32 v126, 0xffff0000, v140
	v_fma_f32 v134, v103, v153, v107
	v_pk_mul_f32 v[126:127], v[98:99], v[126:127]
	v_lshlrev_b32_e32 v160, 16, v235
	v_add_f32_e32 v127, v127, v134
	v_add_f32_e32 v134, v126, v127
	v_mul_f32_e32 v126, 0xbfb8aa3b, v134
	v_exp_f32_e32 v126, v126
	v_mul_f32_e32 v127, v139, v133
	v_mul_f32_e32 v129, v129, v132
	v_mul_f32_e32 v132, v122, v127
	v_add_f32_e32 v122, 1.0, v126
	v_lshlrev_b32_e32 v127, 16, v145
	v_lshlrev_b32_e32 v126, 16, v141
	v_fma_f32 v133, v104, v160, v108
	v_pk_mul_f32 v[126:127], v[166:167], v[126:127]
	v_and_b32_e32 v161, 0xffff0000, v235
	v_add_f32_e32 v127, v127, v133
	v_add_f32_e32 v133, v126, v127
	v_mul_f32_e32 v126, 0xbfb8aa3b, v133
	v_exp_f32_e32 v135, v126
	v_and_b32_e32 v127, 0xffff0000, v145
	v_and_b32_e32 v126, 0xffff0000, v141
	v_fma_f32 v139, v105, v161, v109
	v_pk_mul_f32 v[126:127], v[100:101], v[126:127]
	v_rcp_f32_e32 v122, v122
	v_add_f32_e32 v127, v127, v139
	v_add_f32_e32 v126, v126, v127
	v_mul_f32_e32 v127, 0xbfb8aa3b, v126
	v_exp_f32_e32 v127, v127
	v_mul_f32_e32 v122, v134, v122
	v_add_f32_e32 v134, 1.0, v135
	v_rcp_f32_e32 v134, v134
	v_add_f32_e32 v127, 1.0, v127
	v_rcp_f32_e32 v127, v127
	v_mul_f32_e32 v135, v123, v122
	v_mul_f32_e32 v122, v133, v134
	v_mul_f32_e32 v133, v124, v122
	v_mul_f32_e32 v122, v126, v127
	v_mul_f32_e32 v125, v125, v122
	v_mad_i64_i32 v[126:127], s[0:1], v152, s60, v[136:137]
	v_cvt_pk_bf16_f32 v122, v97, v138
	v_cvt_pk_bf16_f32 v123, v128, v129
	v_cvt_pk_bf16_f32 v124, v132, v135
	v_cvt_pk_bf16_f32 v125, v133, v125
	v_lshl_add_u64 v[132:133], v[126:127], 0, v[168:169]
	v_add_u32_e32 v140, 0x80, v218
	global_store_dwordx4 v[132:133], v[122:125], off nt
	v_add_u32_e32 v138, 0x90, v218
	v_mad_i64_i32 v[134:135], s[0:1], v138, s60, v[220:221]
	v_mad_i64_i32 v[122:123], s[0:1], v140, s60, v[220:221]
	v_add_co_u32_e32 v124, vcc, s62, v122
	s_nop 1
	v_addc_co_u32_e32 v125, vcc, -1, v123, vcc
	global_load_dwordx4 v[142:145], v[124:125], off offset:-2048 nt
	global_load_dword v97, v[202:203], off offset:512
	v_add_co_u32_e32 v124, vcc, s61, v122
	s_waitcnt vmcnt(1)
	v_and_b32_e32 v141, 0xffff0000, v142
	v_addc_co_u32_e32 v125, vcc, -1, v123, vcc
	global_load_dwordx4 v[158:161], v[124:125], off offset:-3072 nt
	global_load_dwordx4 v[162:165], v[122:123], off nt
	v_add_co_u32_e32 v126, vcc, s61, v134
	s_waitcnt vmcnt(2)
	v_fmamk_f32 v97, v97, 0x3a000000, v229
	v_addc_co_u32_e32 v127, vcc, -1, v135, vcc
	global_load_dwordx4 v[122:125], v[134:135], off nt
	s_nop 0
	global_load_dwordx4 v[126:129], v[126:127], off offset:-3072 nt
	v_add_co_u32_e32 v134, vcc, s62, v134
	v_lshlrev_b32_e32 v153, 16, v143
	s_nop 0
	v_addc_co_u32_e32 v135, vcc, -1, v135, vcc
	global_load_dwordx4 v[180:183], v[134:135], off offset:-2048 nt
	global_load_dword v139, v[202:203], off offset:576
	v_rsq_f32_e32 v134, v97
	v_lshlrev_b32_e32 v135, 16, v142
	v_and_b32_e32 v157, 0xffff0000, v143
	v_fma_f32 v141, v115, v141, v119
	v_pk_mul_f32 v[94:95], v[94:95], v[134:135] op_sel_hi:[1,0]
	v_pk_mul_f32 v[92:93], v[92:93], v[134:135] op_sel_hi:[1,0]
	v_fma_f32 v135, v114, v135, v118
	v_lshlrev_b32_e32 v172, 16, v144
	v_and_b32_e32 v97, 0xffff0000, v144
	v_fma_f32 v97, v103, v97, v107
	v_lshlrev_b32_e32 v144, 16, v145
	v_and_b32_e32 v145, 0xffff0000, v145
	s_waitcnt vmcnt(5)
	v_lshlrev_b32_e32 v143, 16, v158
	s_waitcnt vmcnt(4)
; __device__ __forceinline__ unsigned cvt_pk_bf16(float lo, float hi) { unsigned r; asm volatile("v_cvt_pk_bf16_f32 %0, %1, %2" : "=v"(r) : "v"(lo), "v"(hi)); return r; }
;     __device__ __forceinline__ void operator()(const f32x4 (&acc)[2][2][4][2], const Unit& u, int wr, int wc, int fr, int fq) const {
;     ...
;                 for (int m = mp; m < mp + 2; ++m) {
;                     const int row = row0 + ai * HALF + m * 16; const int tpos = row & (SEQ - 1);
;                     const bf16_t* gp = G + (size_t)row * DFF + col0;
;                     g2[m] = *(const u32x4*)gp;
;                     const bool edge = (ai == 0 && m == 0);
;                     g1[m] = *(const u32x4*)(gp - ((!edge || tpos >= 1) ? DFF : 0));
;                     g0[m] = *(const u32x4*)(gp - ((!edge || tpos >= 2) ? 2 * DFF : 0));
;                     rs[m] = ss[row];
;                 }
; #pragma unroll
;                 for (int m = mp; m < mp + 2; ++m) {
;                     const int row = row0 + ai * HALF + m * 16; const int tpos = row & (SEQ - 1);
;                     const u32x4 z4 = {0u, 0u, 0u, 0u};
;                     float f0[8], f1[8], f2[8], o[8];
;                     const bool edge = (ai == 0 && m == 0);
;                     unpack8((!edge || tpos >= 2) ? g0[m] : z4, f0); unpack8((!edge || tpos >= 1) ? g1[m] : z4, f1); unpack8(g2[m], f2);
;                     const float r = __builtin_amdgcn_rsqf(rs[m] * (1.f / DM) + EPS);
;                     const f32x4 v0 = acc[ai][bj][m][0] * r, v1 = acc[ai][bj][m][1] * r;
;                     const float uu[8] = {v0[0], v0[1], v0[2], v0[3], v1[0], v1[1], v1[2], v1[3]};
; #pragma unroll
;                     for (int e = 0; e < 8; ++e) { const float gc = b[e] + w0[e] * f0[e] + w1[e] * f1[e] + w2[e] * f2[e];
;                         const float sg = __builtin_amdgcn_rcpf(1.0f + __builtin_amdgcn_exp2f(-gc * 1.4426950408889634f));
;                         o[e] = gc * sg * uu[e]; }
;                     u32x4 w; w.x = cvt_pk_bf16(o[0], o[1]); w.y = cvt_pk_bf16(o[2], o[3]); w.z = cvt_pk_bf16(o[4], o[5]); w.w = cvt_pk_bf16(o[6], o[7]);
;                     *(u32x4*)(O + (size_t)row * DFF + col0) = w;
;                 }
	v_lshlrev_b32_e32 v142, 16, v162
	v_pk_mul_f32 v[142:143], v[178:179], v[142:143]
	s_nop 0
	v_add_f32_e32 v135, v143, v135
	v_add_f32_e32 v135, v142, v135
	v_mul_f32_e32 v142, 0xbfb8aa3b, v135
	v_exp_f32_e32 v173, v142
	v_and_b32_e32 v143, 0xffff0000, v158
	v_and_b32_e32 v142, 0xffff0000, v162
	v_pk_mul_f32 v[142:143], v[110:111], v[142:143]
	v_pk_mul_f32 v[90:91], v[90:91], v[134:135] op_sel_hi:[1,0]
	v_add_f32_e32 v141, v143, v141
	v_add_f32_e32 v141, v142, v141
	v_mul_f32_e32 v142, 0xbfb8aa3b, v141
	v_exp_f32_e32 v142, v142
	v_add_f32_e32 v143, 1.0, v173
	v_rcp_f32_e32 v143, v143
	v_pk_mul_f32 v[88:89], v[88:89], v[134:135] op_sel_hi:[1,0]
	v_add_f32_e32 v142, 1.0, v142
	v_rcp_f32_e32 v142, v142
	v_mul_f32_e32 v134, v135, v143
	v_mul_f32_e32 v143, v92, v134
	v_lshlrev_b32_e32 v135, 16, v159
	v_lshlrev_b32_e32 v134, 16, v163
	v_mul_f32_e32 v92, v141, v142
	v_fma_f32 v141, v116, v153, v120
	v_pk_mul_f32 v[134:135], v[174:175], v[134:135]
	v_fma_f32 v153, v117, v157, v121
	v_add_f32_e32 v135, v135, v141
	v_add_f32_e32 v141, v134, v135
	v_mul_f32_e32 v134, 0xbfb8aa3b, v141
	v_exp_f32_e32 v142, v134
	v_and_b32_e32 v135, 0xffff0000, v159
	v_and_b32_e32 v134, 0xffff0000, v163
	v_pk_mul_f32 v[134:135], v[112:113], v[134:135]
	v_fma_f32 v157, v102, v172, v106
	v_add_f32_e32 v135, v135, v153
	v_add_f32_e32 v134, v134, v135
	v_mul_f32_e32 v135, 0xbfb8aa3b, v134
	v_exp_f32_e32 v135, v135
	v_mul_f32_e32 v153, v93, v92
	v_add_f32_e32 v92, 1.0, v142
	v_rcp_f32_e32 v142, v92
	v_add_f32_e32 v92, 1.0, v135
	v_rcp_f32_e32 v135, v92
	v_lshlrev_b32_e32 v93, 16, v160
	v_lshlrev_b32_e32 v92, 16, v164
	v_pk_mul_f32 v[92:93], v[170:171], v[92:93]
	v_mul_f32_e32 v134, v134, v135
	v_add_f32_e32 v93, v93, v157
	v_add_f32_e32 v157, v92, v93
	v_mul_f32_e32 v92, 0xbfb8aa3b, v157
	v_exp_f32_e32 v92, v92
	v_mul_f32_e32 v93, v141, v142
	v_mul_f32_e32 v94, v94, v93
	v_and_b32_e32 v93, 0xffff0000, v160
	v_add_f32_e32 v92, 1.0, v92
	v_rcp_f32_e32 v135, v92
	v_and_b32_e32 v92, 0xffff0000, v164
	v_pk_mul_f32 v[92:93], v[98:99], v[92:93]
	v_mul_f32_e32 v95, v95, v134
	v_add_f32_e32 v93, v93, v97
	v_add_f32_e32 v97, v92, v93
	v_mul_f32_e32 v92, 0xbfb8aa3b, v97
	v_exp_f32_e32 v92, v92
	v_mul_f32_e32 v93, v157, v135
	v_mul_f32_e32 v134, v88, v93
	v_lshlrev_b32_e32 v93, 16, v161
	v_add_f32_e32 v88, 1.0, v92
	v_lshlrev_b32_e32 v92, 16, v165
	v_fma_f32 v135, v104, v144, v108
	v_pk_mul_f32 v[92:93], v[166:167], v[92:93]
	v_fma_f32 v142, v105, v145, v109
	v_add_f32_e32 v93, v93, v135
	v_add_f32_e32 v135, v92, v93
	v_mul_f32_e32 v92, 0xbfb8aa3b, v135
	v_exp_f32_e32 v141, v92
	v_and_b32_e32 v93, 0xffff0000, v161
	v_and_b32_e32 v92, 0xffff0000, v165
	v_pk_mul_f32 v[92:93], v[100:101], v[92:93]
	v_rcp_f32_e32 v88, v88
	v_add_f32_e32 v93, v93, v142
	v_add_f32_e32 v92, v92, v93
	v_mul_f32_e32 v93, 0xbfb8aa3b, v92
	v_exp_f32_e32 v93, v93
	v_mul_f32_e32 v88, v97, v88
	v_add_f32_e32 v97, 1.0, v141
	v_rcp_f32_e32 v97, v97
	v_add_f32_e32 v93, 1.0, v93
	v_rcp_f32_e32 v93, v93
	v_mul_f32_e32 v141, v89, v88
	v_mul_f32_e32 v88, v135, v97
	v_mul_f32_e32 v97, v90, v88
	v_mul_f32_e32 v88, v92, v93
	v_mad_i64_i32 v[92:93], s[0:1], v140, s60, v[136:137]
	v_mul_f32_e32 v91, v91, v88
	v_cvt_pk_bf16_f32 v88, v143, v153
	v_cvt_pk_bf16_f32 v89, v94, v95
	v_cvt_pk_bf16_f32 v90, v134, v141
	v_lshl_add_u64 v[134:135], v[92:93], 0, v[168:169]
	v_cvt_pk_bf16_f32 v91, v97, v91
	global_store_dwordx4 v[134:135], v[88:91], off nt
	s_waitcnt vmcnt(2)
	v_and_b32_e32 v92, 0xffff0000, v180
	v_fma_f32 v92, v115, v92, v119
	s_waitcnt vmcnt(1)
	v_fmamk_f32 v88, v139, 0x3a000000, v229
	v_rsq_f32_e32 v88, v88
	v_lshlrev_b32_e32 v89, 16, v180
	v_lshlrev_b32_e32 v91, 16, v126
	v_lshlrev_b32_e32 v90, 16, v122
	v_pk_mul_f32 v[86:87], v[86:87], v[88:89] op_sel_hi:[1,0]
	v_pk_mul_f32 v[84:85], v[84:85], v[88:89] op_sel_hi:[1,0]
	v_fma_f32 v89, v114, v89, v118
	v_pk_mul_f32 v[90:91], v[178:179], v[90:91]
	v_lshlrev_b32_e32 v93, 16, v181
	v_add_f32_e32 v89, v91, v89
	v_add_f32_e32 v89, v90, v89
	v_mul_f32_e32 v90, 0xbfb8aa3b, v89
	v_exp_f32_e32 v142, v90
	v_and_b32_e32 v91, 0xffff0000, v126
	v_and_b32_e32 v90, 0xffff0000, v122
	v_pk_mul_f32 v[90:91], v[110:111], v[90:91]
	v_pk_mul_f32 v[82:83], v[82:83], v[88:89] op_sel_hi:[1,0]
	v_add_f32_e32 v91, v91, v92
	v_add_f32_e32 v90, v90, v91
	v_mul_f32_e32 v91, 0xbfb8aa3b, v90
	v_exp_f32_e32 v91, v91
	v_add_f32_e32 v92, 1.0, v142
	v_rcp_f32_e32 v92, v92
	v_pk_mul_f32 v[80:81], v[80:81], v[88:89] op_sel_hi:[1,0]
	v_add_f32_e32 v91, 1.0, v91
	v_rcp_f32_e32 v91, v91
	v_mul_f32_e32 v88, v89, v92
	v_mul_f32_e32 v92, v84, v88
	v_lshlrev_b32_e32 v89, 16, v127
	v_lshlrev_b32_e32 v88, 16, v123
	v_mul_f32_e32 v84, v90, v91
	v_fma_f32 v90, v116, v93, v120
	v_pk_mul_f32 v[88:89], v[174:175], v[88:89]
	v_and_b32_e32 v94, 0xffff0000, v181
	v_add_f32_e32 v89, v89, v90
	v_add_f32_e32 v90, v88, v89
	v_mul_f32_e32 v88, 0xbfb8aa3b, v90
	v_exp_f32_e32 v91, v88
	v_and_b32_e32 v89, 0xffff0000, v127
	v_and_b32_e32 v88, 0xffff0000, v123
	v_fma_f32 v93, v117, v94, v121
	v_pk_mul_f32 v[88:89], v[112:113], v[88:89]
	v_lshlrev_b32_e32 v95, 16, v182
	v_add_f32_e32 v89, v89, v93
	v_add_f32_e32 v88, v88, v89
	v_mul_f32_e32 v89, 0xbfb8aa3b, v88
	v_exp_f32_e32 v89, v89
	v_mul_f32_e32 v93, v85, v84
	v_add_f32_e32 v84, 1.0, v91
	v_rcp_f32_e32 v91, v84
	v_add_f32_e32 v84, 1.0, v89
	v_rcp_f32_e32 v89, v84
	v_lshlrev_b32_e32 v85, 16, v128
	v_lshlrev_b32_e32 v84, 16, v124
	v_fma_f32 v94, v102, v95, v106
	v_pk_mul_f32 v[84:85], v[170:171], v[84:85]
	v_and_b32_e32 v97, 0xffff0000, v182
	v_add_f32_e32 v85, v85, v94
	v_add_f32_e32 v94, v84, v85
	v_mul_f32_e32 v84, 0xbfb8aa3b, v94
	v_exp_f32_e32 v84, v84
	v_mul_f32_e32 v85, v90, v91
; __device__ __forceinline__ unsigned cvt_pk_bf16(float lo, float hi) { unsigned r; asm volatile("v_cvt_pk_bf16_f32 %0, %1, %2" : "=v"(r) : "v"(lo), "v"(hi)); return r; }
;     __device__ __forceinline__ void operator()(const f32x4 (&acc)[2][2][4][2], const Unit& u, int wr, int wc, int fr, int fq) const {
;     ...
;                 for (int m = mp; m < mp + 2; ++m) {
;                     const int row = row0 + ai * HALF + m * 16; const int tpos = row & (SEQ - 1);
;                     const bf16_t* gp = G + (size_t)row * DFF + col0;
;                     g2[m] = *(const u32x4*)gp;
;                     const bool edge = (ai == 0 && m == 0);
;                     g1[m] = *(const u32x4*)(gp - ((!edge || tpos >= 1) ? DFF : 0));
;                     g0[m] = *(const u32x4*)(gp - ((!edge || tpos >= 2) ? 2 * DFF : 0));
;                     rs[m] = ss[row];
;                 }
; #pragma unroll
;                 for (int m = mp; m < mp + 2; ++m) {
;                     const int row = row0 + ai * HALF + m * 16; const int tpos = row & (SEQ - 1);
;                     const u32x4 z4 = {0u, 0u, 0u, 0u};
;                     float f0[8], f1[8], f2[8], o[8];
;                     const bool edge = (ai == 0 && m == 0);
;                     unpack8((!edge || tpos >= 2) ? g0[m] : z4, f0); unpack8((!edge || tpos >= 1) ? g1[m] : z4, f1); unpack8(g2[m], f2);
;                     const float r = __builtin_amdgcn_rsqf(rs[m] * (1.f / DM) + EPS);
;                     const f32x4 v0 = acc[ai][bj][m][0] * r, v1 = acc[ai][bj][m][1] * r;
;                     const float uu[8] = {v0[0], v0[1], v0[2], v0[3], v1[0], v1[1], v1[2], v1[3]};
; #pragma unroll
;                     for (int e = 0; e < 8; ++e) { const float gc = b[e] + w0[e] * f0[e] + w1[e] * f1[e] + w2[e] * f2[e];
;                         const float sg = __builtin_amdgcn_rcpf(1.0f + __builtin_amdgcn_exp2f(-gc * 1.4426950408889634f));
;                         o[e] = gc * sg * uu[e]; }
;                     u32x4 w; w.x = cvt_pk_bf16(o[0], o[1]); w.y = cvt_pk_bf16(o[2], o[3]); w.z = cvt_pk_bf16(o[4], o[5]); w.w = cvt_pk_bf16(o[6], o[7]);
;                     *(u32x4*)(O + (size_t)row * DFF + col0) = w;
;                 }
	v_mul_f32_e32 v86, v86, v85
	v_mul_f32_e32 v88, v88, v89
	v_add_f32_e32 v84, 1.0, v84
	v_rcp_f32_e32 v89, v84
	v_and_b32_e32 v85, 0xffff0000, v128
	v_and_b32_e32 v84, 0xffff0000, v124
	v_fma_f32 v90, v103, v97, v107
	v_pk_mul_f32 v[84:85], v[98:99], v[84:85]
	v_lshlrev_b32_e32 v139, 16, v183
	v_add_f32_e32 v85, v85, v90
	v_add_f32_e32 v90, v84, v85
	v_mul_f32_e32 v84, 0xbfb8aa3b, v90
	v_exp_f32_e32 v84, v84
	v_mul_f32_e32 v85, v94, v89
	v_mul_f32_e32 v87, v87, v88
	v_mul_f32_e32 v88, v80, v85
	v_add_f32_e32 v80, 1.0, v84
	v_lshlrev_b32_e32 v85, 16, v129
	v_lshlrev_b32_e32 v84, 16, v125
	v_fma_f32 v89, v104, v139, v108
	v_pk_mul_f32 v[84:85], v[166:167], v[84:85]
	v_and_b32_e32 v141, 0xffff0000, v183
	v_add_f32_e32 v85, v85, v89
	v_add_f32_e32 v89, v84, v85
	v_mul_f32_e32 v84, 0xbfb8aa3b, v89
	v_exp_f32_e32 v91, v84
	v_and_b32_e32 v85, 0xffff0000, v129
	v_and_b32_e32 v84, 0xffff0000, v125
	v_fma_f32 v94, v105, v141, v109
	v_pk_mul_f32 v[84:85], v[100:101], v[84:85]
	v_rcp_f32_e32 v80, v80
	v_add_f32_e32 v85, v85, v94
	v_add_f32_e32 v84, v84, v85
	v_mul_f32_e32 v85, 0xbfb8aa3b, v84
	v_exp_f32_e32 v85, v85
	v_mul_f32_e32 v80, v90, v80
	v_add_f32_e32 v90, 1.0, v91
	v_rcp_f32_e32 v90, v90
	v_add_f32_e32 v85, 1.0, v85
	v_rcp_f32_e32 v85, v85
	v_mul_f32_e32 v91, v81, v80
	v_mul_f32_e32 v80, v89, v90
	v_mul_f32_e32 v89, v82, v80
	v_mul_f32_e32 v80, v84, v85
	v_mad_i64_i32 v[84:85], s[0:1], v138, s60, v[136:137]
	v_mul_f32_e32 v83, v83, v80
	v_cvt_pk_bf16_f32 v80, v92, v93
	v_cvt_pk_bf16_f32 v81, v86, v87
	v_lshl_add_u64 v[122:123], v[84:85], 0, v[168:169]
	v_add_u32_e32 v141, 0xa0, v218
	v_cvt_pk_bf16_f32 v82, v88, v91
	v_cvt_pk_bf16_f32 v83, v89, v83
	global_store_dwordx4 v[122:123], v[80:83], off nt
	v_add_u32_e32 v139, 0xb0, v218
	v_mad_i64_i32 v[128:129], s[0:1], v139, s60, v[220:221]
	v_mad_i64_i32 v[80:81], s[0:1], v141, s60, v[220:221]
	v_add_co_u32_e32 v82, vcc, s62, v80
	s_nop 1
	v_addc_co_u32_e32 v83, vcc, -1, v81, vcc
	global_load_dwordx4 v[88:91], v[82:83], off offset:-2048 nt
	global_load_dword v97, v[202:203], off offset:640
	v_add_co_u32_e32 v82, vcc, s61, v80
	s_waitcnt vmcnt(1)
	v_and_b32_e32 v153, 0xffff0000, v88
	v_addc_co_u32_e32 v83, vcc, -1, v81, vcc
	global_load_dwordx4 v[92:95], v[82:83], off offset:-3072 nt
	global_load_dwordx4 v[124:127], v[80:81], off nt
	v_add_co_u32_e32 v84, vcc, s61, v128
	v_lshlrev_b32_e32 v159, 16, v90
	s_nop 0
	v_addc_co_u32_e32 v85, vcc, -1, v129, vcc
	global_load_dwordx4 v[80:83], v[128:129], off nt
	s_nop 0
	global_load_dwordx4 v[84:87], v[84:85], off offset:-3072 nt
	v_add_co_u32_e32 v128, vcc, s62, v128
	v_lshlrev_b32_e32 v160, 16, v91
	s_nop 0
	v_addc_co_u32_e32 v129, vcc, -1, v129, vcc
	global_load_dwordx4 v[142:145], v[128:129], off offset:-2048 nt
	s_nop 0
	global_load_dword v128, v[202:203], off offset:704
	v_lshlrev_b32_e32 v129, 16, v88
	s_waitcnt vmcnt(6)
	v_fmamk_f32 v88, v97, 0x3a000000, v229
	v_rsq_f32_e32 v88, v88
	v_and_b32_e32 v97, 0xffff0000, v90
	v_and_b32_e32 v161, 0xffff0000, v91
	v_lshlrev_b32_e32 v157, 16, v89
	v_and_b32_e32 v158, 0xffff0000, v89
	v_pk_mul_f32 v[78:79], v[78:79], v[88:89] op_sel_hi:[1,0]
	v_pk_mul_f32 v[76:77], v[76:77], v[88:89] op_sel_hi:[1,0]
	v_fma_f32 v89, v114, v129, v118
	v_fma_f32 v153, v115, v153, v119
	s_waitcnt vmcnt(5)
	v_lshlrev_b32_e32 v91, 16, v92
	s_waitcnt vmcnt(4)
	v_lshlrev_b32_e32 v90, 16, v124
	v_pk_mul_f32 v[90:91], v[178:179], v[90:91]
	s_nop 0
	v_add_f32_e32 v89, v91, v89
	v_add_f32_e32 v89, v90, v89
	v_mul_f32_e32 v90, 0xbfb8aa3b, v89
	v_exp_f32_e32 v129, v90
	v_and_b32_e32 v91, 0xffff0000, v92
	v_and_b32_e32 v90, 0xffff0000, v124
	v_pk_mul_f32 v[90:91], v[110:111], v[90:91]
	v_add_f32_e32 v92, 1.0, v129
	v_add_f32_e32 v91, v91, v153
	v_add_f32_e32 v90, v90, v91
	v_mul_f32_e32 v91, 0xbfb8aa3b, v90
	v_exp_f32_e32 v91, v91
	v_rcp_f32_e32 v92, v92
	v_pk_mul_f32 v[74:75], v[74:75], v[88:89] op_sel_hi:[1,0]
	v_pk_mul_f32 v[72:73], v[72:73], v[88:89] op_sel_hi:[1,0]
	v_add_f32_e32 v91, 1.0, v91
	v_rcp_f32_e32 v91, v91
	v_mul_f32_e32 v88, v89, v92
	v_mul_f32_e32 v92, v76, v88
	v_lshlrev_b32_e32 v89, 16, v93
	v_lshlrev_b32_e32 v88, 16, v125
	v_mul_f32_e32 v76, v90, v91
	v_fma_f32 v90, v116, v157, v120
	v_pk_mul_f32 v[88:89], v[174:175], v[88:89]
	v_fma_f32 v124, v117, v158, v121
	v_add_f32_e32 v89, v89, v90
	v_add_f32_e32 v90, v88, v89
	v_mul_f32_e32 v88, 0xbfb8aa3b, v90
	v_exp_f32_e32 v91, v88
	v_and_b32_e32 v89, 0xffff0000, v93
	v_and_b32_e32 v88, 0xffff0000, v125
	v_pk_mul_f32 v[88:89], v[112:113], v[88:89]
	v_mul_f32_e32 v93, v77, v76
	v_add_f32_e32 v89, v89, v124
	v_add_f32_e32 v88, v88, v89
	v_mul_f32_e32 v89, 0xbfb8aa3b, v88
	v_exp_f32_e32 v89, v89
	v_add_f32_e32 v76, 1.0, v91
	v_rcp_f32_e32 v91, v76
	v_lshlrev_b32_e32 v77, 16, v94
	v_add_f32_e32 v76, 1.0, v89
	v_rcp_f32_e32 v89, v76
	v_lshlrev_b32_e32 v76, 16, v126
	v_fma_f32 v124, v102, v159, v106
	v_pk_mul_f32 v[76:77], v[170:171], v[76:77]
	v_mul_f32_e32 v88, v88, v89
	v_add_f32_e32 v77, v77, v124
	v_add_f32_e32 v124, v76, v77
	v_mul_f32_e32 v76, 0xbfb8aa3b, v124
	v_exp_f32_e32 v76, v76
	v_mul_f32_e32 v77, v90, v91
	v_mul_f32_e32 v78, v78, v77
	v_and_b32_e32 v77, 0xffff0000, v94
	v_add_f32_e32 v76, 1.0, v76
	v_rcp_f32_e32 v89, v76
	v_and_b32_e32 v76, 0xffff0000, v126
	v_fma_f32 v90, v103, v97, v107
	v_pk_mul_f32 v[76:77], v[98:99], v[76:77]
	v_mul_f32_e32 v79, v79, v88
	v_add_f32_e32 v77, v77, v90
	v_add_f32_e32 v90, v76, v77
	v_mul_f32_e32 v76, 0xbfb8aa3b, v90
	v_exp_f32_e32 v76, v76
	v_mul_f32_e32 v77, v124, v89
	v_mul_f32_e32 v88, v72, v77
	v_lshlrev_b32_e32 v77, 16, v95
	v_add_f32_e32 v72, 1.0, v76
	v_lshlrev_b32_e32 v76, 16, v127
	v_fma_f32 v89, v104, v160, v108
	v_pk_mul_f32 v[76:77], v[166:167], v[76:77]
	v_fma_f32 v94, v105, v161, v109
	v_add_f32_e32 v77, v77, v89
	v_add_f32_e32 v89, v76, v77
	v_mul_f32_e32 v76, 0xbfb8aa3b, v89
	v_exp_f32_e32 v91, v76
	v_and_b32_e32 v77, 0xffff0000, v95
	v_and_b32_e32 v76, 0xffff0000, v127
	v_pk_mul_f32 v[76:77], v[100:101], v[76:77]
	v_rcp_f32_e32 v72, v72
	v_add_f32_e32 v77, v77, v94
	v_add_f32_e32 v76, v76, v77
	v_mul_f32_e32 v77, 0xbfb8aa3b, v76
	v_exp_f32_e32 v77, v77
	v_mul_f32_e32 v72, v90, v72
	v_add_f32_e32 v90, 1.0, v91
	v_rcp_f32_e32 v90, v90
	v_add_f32_e32 v77, 1.0, v77
	v_rcp_f32_e32 v77, v77
	v_mul_f32_e32 v91, v73, v72
	v_mul_f32_e32 v72, v89, v90
	v_mul_f32_e32 v89, v74, v72
	v_mul_f32_e32 v72, v76, v77
	v_mad_i64_i32 v[76:77], s[0:1], v141, s60, v[136:137]
	v_mul_f32_e32 v75, v75, v72
	v_cvt_pk_bf16_f32 v72, v92, v93
	v_lshl_add_u64 v[124:125], v[76:77], 0, v[168:169]
	v_cvt_pk_bf16_f32 v73, v78, v79
	v_cvt_pk_bf16_f32 v74, v88, v91
	v_cvt_pk_bf16_f32 v75, v89, v75
	global_store_dwordx4 v[124:125], v[72:75], off nt
	s_waitcnt vmcnt(2)
; __device__ __forceinline__ unsigned cvt_pk_bf16(float lo, float hi) { unsigned r; asm volatile("v_cvt_pk_bf16_f32 %0, %1, %2" : "=v"(r) : "v"(lo), "v"(hi)); return r; }
;     __device__ __forceinline__ void operator()(const f32x4 (&acc)[2][2][4][2], const Unit& u, int wr, int wc, int fr, int fq) const {
;     ...
;             const int col0 = u.pn * BM + bj * HALF + wc * 32 + 8 * fq;
;             float w0[8], w1[8], w2[8], b[8];
; #pragma unroll
;             for (int e = 0; e < 8; e += 4) {
;                 *(f32x4*)(w0 + e) = *(const f32x4*)(cw + col0 + e); *(f32x4*)(w1 + e) = *(const f32x4*)(cw + DFF + col0 + e);
;                 *(f32x4*)(w2 + e) = *(const f32x4*)(cw + 2 * DFF + col0 + e); *(f32x4*)(b + e) = *(const f32x4*)(cb + col0 + e); }
; #pragma unroll
;             for (int ai = 0; ai < 2; ++ai) {
; #pragma unroll
;               for (int mp = 0; mp < 4; mp += 2) {
;                 u32x4 g0[4], g1[4], g2[4]; float rs[4];
; #pragma unroll
;                 for (int m = mp; m < mp + 2; ++m) {
;                     const int row = row0 + ai * HALF + m * 16; const int tpos = row & (SEQ - 1);
;                     const bf16_t* gp = G + (size_t)row * DFF + col0;
;                     g2[m] = *(const u32x4*)gp;
;                     const bool edge = (ai == 0 && m == 0);
;                     g1[m] = *(const u32x4*)(gp - ((!edge || tpos >= 1) ? DFF : 0));
;                     g0[m] = *(const u32x4*)(gp - ((!edge || tpos >= 2) ? 2 * DFF : 0));
;                     rs[m] = ss[row];
;     ...
;                     const float r = __builtin_amdgcn_rsqf(rs[m] * (1.f / DM) + EPS);
;                     const f32x4 v0 = acc[ai][bj][m][0] * r, v1 = acc[ai][bj][m][1] * r;
;                     const float uu[8] = {v0[0], v0[1], v0[2], v0[3], v1[0], v1[1], v1[2], v1[3]};
; #pragma unroll
;                     for (int e = 0; e < 8; ++e) { const float gc = b[e] + w0[e] * f0[e] + w1[e] * f1[e] + w2[e] * f2[e];
;                         const float sg = __builtin_amdgcn_rcpf(1.0f + __builtin_amdgcn_exp2f(-gc * 1.4426950408889634f));
;                         o[e] = gc * sg * uu[e]; }
;                     u32x4 w; w.x = cvt_pk_bf16(o[0], o[1]); w.y = cvt_pk_bf16(o[2], o[3]); w.z = cvt_pk_bf16(o[4], o[5]); w.w = cvt_pk_bf16(o[6], o[7]);
;                     *(u32x4*)(O + (size_t)row * DFF + col0) = w;
	v_and_b32_e32 v76, 0xffff0000, v142
	v_fma_f32 v76, v115, v76, v119
	s_waitcnt vmcnt(1)
	v_fmamk_f32 v72, v128, 0x3a000000, v229
	v_rsq_f32_e32 v72, v72
	v_lshlrev_b32_e32 v73, 16, v142
	v_lshlrev_b32_e32 v75, 16, v84
	v_lshlrev_b32_e32 v74, 16, v80
	v_pk_mul_f32 v[70:71], v[70:71], v[72:73] op_sel_hi:[1,0]
	v_pk_mul_f32 v[68:69], v[68:69], v[72:73] op_sel_hi:[1,0]
	v_fma_f32 v73, v114, v73, v118
	v_pk_mul_f32 v[74:75], v[178:179], v[74:75]
	v_lshlrev_b32_e32 v77, 16, v143
	v_add_f32_e32 v73, v75, v73
	v_add_f32_e32 v73, v74, v73
	v_mul_f32_e32 v74, 0xbfb8aa3b, v73
	v_exp_f32_e32 v91, v74
	v_and_b32_e32 v75, 0xffff0000, v84
	v_and_b32_e32 v74, 0xffff0000, v80
	v_pk_mul_f32 v[74:75], v[110:111], v[74:75]
	v_pk_mul_f32 v[66:67], v[66:67], v[72:73] op_sel_hi:[1,0]
	v_add_f32_e32 v75, v75, v76
	v_add_f32_e32 v74, v74, v75
	v_mul_f32_e32 v75, 0xbfb8aa3b, v74
	v_exp_f32_e32 v75, v75
	v_add_f32_e32 v76, 1.0, v91
	v_rcp_f32_e32 v76, v76
	v_pk_mul_f32 v[64:65], v[64:65], v[72:73] op_sel_hi:[1,0]
	v_add_f32_e32 v75, 1.0, v75
	v_rcp_f32_e32 v75, v75
	v_mul_f32_e32 v72, v73, v76
	v_mul_f32_e32 v76, v68, v72
	v_lshlrev_b32_e32 v73, 16, v85
	v_lshlrev_b32_e32 v72, 16, v81
	v_mul_f32_e32 v68, v74, v75
	v_fma_f32 v74, v116, v77, v120
	v_pk_mul_f32 v[72:73], v[174:175], v[72:73]
	v_and_b32_e32 v78, 0xffff0000, v143
	v_add_f32_e32 v73, v73, v74
	v_add_f32_e32 v74, v72, v73
	v_mul_f32_e32 v72, 0xbfb8aa3b, v74
	v_exp_f32_e32 v75, v72
	v_and_b32_e32 v73, 0xffff0000, v85
	v_and_b32_e32 v72, 0xffff0000, v81
	v_fmac_f32_e32 v121, v117, v78
	v_pk_mul_f32 v[72:73], v[112:113], v[72:73]
	v_mul_f32_e32 v77, v69, v68
	v_add_f32_e32 v73, v73, v121
	v_add_f32_e32 v72, v72, v73
	v_mul_f32_e32 v73, 0xbfb8aa3b, v72
	v_exp_f32_e32 v73, v73
	v_add_f32_e32 v68, 1.0, v75
	v_rcp_f32_e32 v75, v68
	v_lshlrev_b32_e32 v79, 16, v144
	v_add_f32_e32 v68, 1.0, v73
	v_rcp_f32_e32 v73, v68
	v_lshlrev_b32_e32 v69, 16, v86
	v_lshlrev_b32_e32 v68, 16, v82
	v_fma_f32 v78, v102, v79, v106
	v_pk_mul_f32 v[68:69], v[170:171], v[68:69]
	v_and_b32_e32 v88, 0xffff0000, v144
	v_add_f32_e32 v69, v69, v78
	v_add_f32_e32 v78, v68, v69
	v_mul_f32_e32 v68, 0xbfb8aa3b, v78
	v_exp_f32_e32 v68, v68
	v_mul_f32_e32 v69, v74, v75
	v_mul_f32_e32 v70, v70, v69
	v_mul_f32_e32 v72, v72, v73
	v_add_f32_e32 v68, 1.0, v68
	v_rcp_f32_e32 v73, v68
	v_and_b32_e32 v69, 0xffff0000, v86
	v_and_b32_e32 v68, 0xffff0000, v82
	v_fma_f32 v74, v103, v88, v107
	v_pk_mul_f32 v[68:69], v[98:99], v[68:69]
	v_lshlrev_b32_e32 v89, 16, v145
	v_add_f32_e32 v69, v69, v74
	v_add_f32_e32 v74, v68, v69
	v_mul_f32_e32 v68, 0xbfb8aa3b, v74
	v_exp_f32_e32 v68, v68
	v_mul_f32_e32 v69, v78, v73
	v_mul_f32_e32 v71, v71, v72
	v_mul_f32_e32 v72, v64, v69
	v_add_f32_e32 v64, 1.0, v68
	v_lshlrev_b32_e32 v69, 16, v87
	v_lshlrev_b32_e32 v68, 16, v83
	v_fma_f32 v73, v104, v89, v108
	v_pk_mul_f32 v[68:69], v[166:167], v[68:69]
	v_and_b32_e32 v90, 0xffff0000, v145
	v_add_f32_e32 v69, v69, v73
	v_add_f32_e32 v73, v68, v69
	v_mul_f32_e32 v68, 0xbfb8aa3b, v73
	v_exp_f32_e32 v75, v68
	v_and_b32_e32 v69, 0xffff0000, v87
	v_and_b32_e32 v68, 0xffff0000, v83
	v_fmac_f32_e32 v109, v105, v90
	v_pk_mul_f32 v[68:69], v[100:101], v[68:69]
	v_rcp_f32_e32 v64, v64
	v_add_f32_e32 v69, v69, v109
	v_add_f32_e32 v68, v68, v69
	v_mul_f32_e32 v69, 0xbfb8aa3b, v68
	v_exp_f32_e32 v69, v69
	v_mul_f32_e32 v64, v74, v64
	v_add_f32_e32 v74, 1.0, v75
	v_rcp_f32_e32 v74, v74
	v_add_f32_e32 v69, 1.0, v69
	v_rcp_f32_e32 v69, v69
	v_mul_f32_e32 v75, v65, v64
	v_mul_f32_e32 v64, v73, v74
	v_or_b32_e32 v88, 0x80, v208
	v_mul_f32_e32 v73, v66, v64
	v_mul_f32_e32 v64, v68, v69
	v_mad_i64_i32 v[68:69], s[0:1], v139, s60, v[136:137]
	v_ashrrev_i32_e32 v89, 31, v88
	v_mul_f32_e32 v67, v67, v64
	v_cvt_pk_bf16_f32 v64, v76, v77
	v_cvt_pk_bf16_f32 v65, v70, v71
	v_lshl_add_u64 v[120:121], v[68:69], 0, v[168:169]
	v_lshl_add_u64 v[90:91], s[18:19], 0, v[216:217]
	v_lshlrev_b64 v[126:127], 1, v[88:89]
	v_cvt_pk_bf16_f32 v66, v72, v75
	v_cvt_pk_bf16_f32 v67, v73, v67
	global_store_dwordx4 v[120:121], v[64:67], off nt
	v_lshl_add_u64 v[128:129], v[90:91], 0, v[126:127]
	v_mov_b32_e32 v97, 0
	v_lshlrev_b64 v[64:65], 2, v[88:89]
	v_lshl_add_u64 v[88:89], v[210:211], 1, v[90:91]
	v_lshl_add_u64 v[90:91], s[18:19], 0, v[214:215]
	v_lshl_add_u64 v[72:73], s[28:29], 0, v[64:65]
	v_lshl_add_u64 v[74:75], s[30:31], 0, v[64:65]
	v_lshl_add_u64 v[92:93], v[90:91], 0, v[126:127]
	global_load_dwordx4 v[68:71], v[206:207], off offset:528
	global_load_dwordx4 v[80:83], v[206:207], off offset:512
	global_load_dwordx4 v[64:67], v[72:73], off offset:16
	global_load_dwordx4 v[76:79], v[72:73], off nt
	global_load_dwordx4 v[104:107], v[74:75], off offset:16
	global_load_dwordx4 v[112:115], v[74:75], off nt
	s_nop 0
	global_load_dwordx4 v[72:75], v[204:205], off offset:528
	global_load_dwordx4 v[84:87], v[204:205], off offset:512
	v_add_co_u32_e32 v94, vcc, 0xffffe000, v92
	v_lshl_add_u64 v[88:89], v[88:89], 0, v[126:127]
	s_nop 0
	v_addc_co_u32_e32 v95, vcc, -1, v93, vcc
	v_add_co_u32_e32 v98, vcc, 0xffffb000, v92
	global_load_dwordx4 v[116:119], v[88:89], off nt
	s_nop 0
	global_load_dwordx4 v[88:91], v[92:93], off nt
	v_addc_co_u32_e32 v99, vcc, -1, v93, vcc
	global_load_dwordx4 v[92:95], v[94:95], off offset:-3072 nt
	s_nop 0
	global_load_dwordx4 v[100:103], v[98:99], off offset:-2048 nt
	global_load_dwordx4 v[108:111], v[128:129], off nt
	global_load_dword v137, v[202:203], off
	global_load_dword v136, v[212:213], off
	v_mov_b32_e32 v98, 0
	v_mov_b32_e32 v99, 0
	s_and_saveexec_b64 s[0:1], s[8:9]
	s_cbranch_execz .LBB0_1010
	v_add_co_u32_e32 v96, vcc, 0xffffb000, v128
	s_nop 1
	v_addc_co_u32_e32 v97, vcc, -1, v129, vcc
	global_load_dwordx4 v[96:99], v[96:97], off offset:-2048 nt
; __device__ __forceinline__ unsigned cvt_pk_bf16(float lo, float hi) { unsigned r; asm volatile("v_cvt_pk_bf16_f32 %0, %1, %2" : "=v"(r) : "v"(lo), "v"(hi)); return r; }
;     __device__ __forceinline__ void operator()(const f32x4 (&acc)[2][2][4][2], const Unit& u, int wr, int wc, int fr, int fq) const {
;     ...
;                 for (int m = mp; m < mp + 2; ++m) {
;                     const int row = row0 + ai * HALF + m * 16; const int tpos = row & (SEQ - 1);
;                     const u32x4 z4 = {0u, 0u, 0u, 0u};
;                     float f0[8], f1[8], f2[8], o[8];
;                     const bool edge = (ai == 0 && m == 0);
;                     unpack8((!edge || tpos >= 2) ? g0[m] : z4, f0); unpack8((!edge || tpos >= 1) ? g1[m] : z4, f1); unpack8(g2[m], f2);
;                     const float r = __builtin_amdgcn_rsqf(rs[m] * (1.f / DM) + EPS);
;                     const f32x4 v0 = acc[ai][bj][m][0] * r, v1 = acc[ai][bj][m][1] * r;
;                     const float uu[8] = {v0[0], v0[1], v0[2], v0[3], v1[0], v1[1], v1[2], v1[3]};
; #pragma unroll
;                     for (int e = 0; e < 8; ++e) { const float gc = b[e] + w0[e] * f0[e] + w1[e] * f1[e] + w2[e] * f2[e];
;                         const float sg = __builtin_amdgcn_rcpf(1.0f + __builtin_amdgcn_exp2f(-gc * 1.4426950408889634f));
;                         o[e] = gc * sg * uu[e]; }
;                     u32x4 w; w.x = cvt_pk_bf16(o[0], o[1]); w.y = cvt_pk_bf16(o[2], o[3]); w.z = cvt_pk_bf16(o[4], o[5]); w.w = cvt_pk_bf16(o[6], o[7]);
;                     *(u32x4*)(O + (size_t)row * DFF + col0) = w;
;                 }
.LBB0_1010:
	s_or_b64 exec, exec, s[0:1]
	s_waitcnt vmcnt(0)
	v_lshlrev_b32_e32 v142, 16, v96
	v_and_b32_e32 v143, 0xffff0000, v96
	v_fmamk_f32 v96, v137, 0x3a000000, v229
	v_rsq_f32_e32 v96, v96
	v_lshlrev_b32_e32 v144, 16, v97
	v_and_b32_e32 v145, 0xffff0000, v97
	v_cndmask_b32_e64 v97, v116, 0, s[6:7]
	v_mad_i64_i32 v[128:129], s[0:1], v156, s60, 0
	v_lshlrev_b32_e32 v153, 16, v98
	v_and_b32_e32 v156, 0xffff0000, v98
	v_lshlrev_b32_e32 v157, 16, v99
	v_and_b32_e32 v158, 0xffff0000, v99
	v_cndmask_b32_e64 v137, v117, 0, s[6:7]
	v_pk_mul_f32 v[98:99], v[60:61], v[96:97] op_sel_hi:[1,0]
	v_lshlrev_b32_e32 v117, 16, v97
	v_lshlrev_b32_e32 v116, 16, v108
	v_mov_b32_e32 v60, v112
	v_mov_b32_e32 v61, v76
	v_fma_f32 v142, v80, v142, v84
	v_pk_mul_f32 v[116:117], v[60:61], v[116:117]
	v_fma_f32 v143, v81, v143, v85
	v_add_f32_e32 v76, v117, v142
	v_add_f32_e32 v142, v116, v76
	v_mul_f32_e32 v76, 0xbfb8aa3b, v142
	v_exp_f32_e32 v159, v76
	v_and_b32_e32 v117, 0xffff0000, v97
	v_and_b32_e32 v116, 0xffff0000, v108
	v_mov_b32_e32 v76, v113
	v_pk_mul_f32 v[112:113], v[76:77], v[116:117]
	v_pk_mul_f32 v[62:63], v[62:63], v[96:97] op_sel_hi:[1,0]
	v_add_f32_e32 v97, v113, v143
	v_add_f32_e32 v108, v112, v97
	v_mul_f32_e32 v97, 0xbfb8aa3b, v108
	v_exp_f32_e32 v97, v97
	v_fma_f32 v117, v83, v145, v87
	v_cndmask_b32_e64 v118, v118, 0, s[6:7]
	v_cndmask_b32_e64 v119, v119, 0, s[6:7]
	v_pk_mul_f32 v[112:113], v[58:59], v[96:97] op_sel_hi:[1,0]
	v_add_f32_e32 v58, 1.0, v159
	v_rcp_f32_e32 v58, v58
	v_add_f32_e32 v59, 1.0, v97
	v_rcp_f32_e32 v59, v59
	v_pk_mul_f32 v[96:97], v[56:57], v[96:97] op_sel_hi:[1,0]
	v_mul_f32_e32 v56, v142, v58
	v_mul_f32_e32 v116, v98, v56
	v_mul_f32_e32 v98, v108, v59
	v_lshlrev_b32_e32 v59, 16, v137
	v_lshlrev_b32_e32 v58, 16, v109
	v_mov_b32_e32 v56, v114
	v_mov_b32_e32 v57, v78
	v_fma_f32 v108, v82, v144, v86
	v_pk_mul_f32 v[58:59], v[56:57], v[58:59]
	v_mov_b32_e32 v78, v115
	v_add_f32_e32 v59, v59, v108
	v_add_f32_e32 v108, v58, v59
	v_mul_f32_e32 v58, 0xbfb8aa3b, v108
	v_exp_f32_e32 v114, v58
	v_and_b32_e32 v59, 0xffff0000, v137
	v_and_b32_e32 v58, 0xffff0000, v109
	v_pk_mul_f32 v[58:59], v[78:79], v[58:59]
	v_mul_f32_e32 v115, v99, v98
	v_add_f32_e32 v59, v59, v117
	v_add_f32_e32 v109, v58, v59
	v_mul_f32_e32 v58, 0xbfb8aa3b, v109
	v_exp_f32_e32 v58, v58
	v_add_f32_e32 v59, 1.0, v114
	v_rcp_f32_e32 v114, v59
	v_lshlrev_b32_e32 v99, 16, v118
	v_add_f32_e32 v58, 1.0, v58
	v_rcp_f32_e32 v117, v58
	v_lshlrev_b32_e32 v98, 16, v110
	v_mov_b32_e32 v58, v104
	v_mov_b32_e32 v59, v64
	v_fma_f32 v137, v68, v153, v72
	v_pk_mul_f32 v[98:99], v[58:59], v[98:99]
	s_nop 0
	v_add_f32_e32 v64, v99, v137
	v_add_f32_e32 v104, v98, v64
	v_mul_f32_e32 v64, 0xbfb8aa3b, v104
	v_exp_f32_e32 v64, v64
	v_mul_f32_e32 v98, v108, v114
	v_mul_f32_e32 v108, v62, v98
	v_mul_f32_e32 v62, v109, v117
	v_add_f32_e32 v64, 1.0, v64
	v_rcp_f32_e32 v109, v64
	v_and_b32_e32 v99, 0xffff0000, v118
	v_and_b32_e32 v98, 0xffff0000, v110
	v_mov_b32_e32 v64, v105
	v_fma_f32 v114, v69, v156, v73
	v_pk_mul_f32 v[98:99], v[64:65], v[98:99]
	v_mul_f32_e32 v110, v63, v62
	v_add_f32_e32 v99, v99, v114
	v_add_f32_e32 v105, v98, v99
	v_mul_f32_e32 v98, 0xbfb8aa3b, v105
	v_exp_f32_e32 v98, v98
	v_mul_f32_e32 v62, v104, v109
	v_mul_f32_e32 v104, v96, v62
	v_lshlrev_b32_e32 v99, 16, v119
	v_add_f32_e32 v62, 1.0, v98
	v_rcp_f32_e32 v96, v62
	v_lshlrev_b32_e32 v98, 16, v111
	v_mov_b32_e32 v62, v106
	v_mov_b32_e32 v63, v66
	v_fma_f32 v109, v70, v157, v74
	v_pk_mul_f32 v[98:99], v[62:63], v[98:99]
	v_fma_f32 v114, v71, v158, v75
	v_add_f32_e32 v66, v99, v109
	v_add_f32_e32 v106, v98, v66
	v_mul_f32_e32 v66, 0xbfb8aa3b, v106
	v_exp_f32_e32 v109, v66
	v_and_b32_e32 v99, 0xffff0000, v119
	v_and_b32_e32 v98, 0xffff0000, v111
	v_mov_b32_e32 v66, v107
	v_pk_mul_f32 v[98:99], v[66:67], v[98:99]
	v_mul_f32_e32 v96, v105, v96
	v_add_f32_e32 v99, v99, v114
	v_add_f32_e32 v98, v98, v99
	v_mul_f32_e32 v99, 0xbfb8aa3b, v98
	v_exp_f32_e32 v99, v99
	v_add_f32_e32 v105, 1.0, v109
	v_rcp_f32_e32 v105, v105
	v_mul_f32_e32 v107, v97, v96
	v_add_f32_e32 v99, 1.0, v99
	v_rcp_f32_e32 v99, v99
	v_mul_f32_e32 v96, v106, v105
	v_mul_f32_e32 v105, v112, v96
	v_lshlrev_b32_e32 v106, 16, v103
	v_mul_f32_e32 v96, v98, v99
	v_mul_f32_e32 v99, v113, v96
	v_cvt_pk_bf16_f32 v96, v116, v115
	v_cvt_pk_bf16_f32 v97, v108, v110
	v_cvt_pk_bf16_f32 v98, v104, v107
	v_cvt_pk_bf16_f32 v99, v105, v99
	global_store_dwordx4 v[146:147], v[96:99], off offset:256 nt
	v_lshlrev_b32_e32 v104, 16, v101
	v_and_b32_e32 v101, 0xffff0000, v101
	v_fmamk_f32 v96, v136, 0x3a000000, v229
	v_rsq_f32_e32 v96, v96
	v_lshlrev_b32_e32 v97, 16, v100
	v_lshlrev_b32_e32 v99, 16, v92
	v_lshlrev_b32_e32 v98, 16, v88
	v_pk_mul_f32 v[54:55], v[54:55], v[96:97] op_sel_hi:[1,0]
	v_pk_mul_f32 v[52:53], v[52:53], v[96:97] op_sel_hi:[1,0]
	v_fma_f32 v97, v80, v97, v84
	v_pk_mul_f32 v[98:99], v[60:61], v[98:99]
	v_and_b32_e32 v100, 0xffff0000, v100
	v_add_f32_e32 v97, v99, v97
	v_add_f32_e32 v97, v98, v97
	v_mul_f32_e32 v98, 0xbfb8aa3b, v97
	v_exp_f32_e32 v107, v98
	v_and_b32_e32 v99, 0xffff0000, v92
	v_and_b32_e32 v98, 0xffff0000, v88
	v_fma_f32 v100, v81, v100, v85
	v_pk_mul_f32 v[98:99], v[76:77], v[98:99]
	v_pk_mul_f32 v[50:51], v[50:51], v[96:97] op_sel_hi:[1,0]
	v_add_f32_e32 v88, v99, v100
	v_add_f32_e32 v88, v98, v88
	v_mul_f32_e32 v92, 0xbfb8aa3b, v88
	v_exp_f32_e32 v92, v92
	v_add_f32_e32 v98, 1.0, v107
	v_rcp_f32_e32 v98, v98
	v_pk_mul_f32 v[48:49], v[48:49], v[96:97] op_sel_hi:[1,0]
	v_add_f32_e32 v92, 1.0, v92
	v_rcp_f32_e32 v92, v92
	v_mul_f32_e32 v96, v97, v98
	v_mul_f32_e32 v98, v52, v96
	v_lshlrev_b32_e32 v97, 16, v93
	v_lshlrev_b32_e32 v96, 16, v89
; __device__ __forceinline__ unsigned cvt_pk_bf16(float lo, float hi) { unsigned r; asm volatile("v_cvt_pk_bf16_f32 %0, %1, %2" : "=v"(r) : "v"(lo), "v"(hi)); return r; }
;     __device__ __forceinline__ void operator()(const f32x4 (&acc)[2][2][4][2], const Unit& u, int wr, int wc, int fr, int fq) const {
;     ...
;                 for (int m = mp; m < mp + 2; ++m) {
;                     const int row = row0 + ai * HALF + m * 16; const int tpos = row & (SEQ - 1);
;                     const bf16_t* gp = G + (size_t)row * DFF + col0;
;                     g2[m] = *(const u32x4*)gp;
;                     const bool edge = (ai == 0 && m == 0);
;                     g1[m] = *(const u32x4*)(gp - ((!edge || tpos >= 1) ? DFF : 0));
;                     g0[m] = *(const u32x4*)(gp - ((!edge || tpos >= 2) ? 2 * DFF : 0));
;                     rs[m] = ss[row];
;                 }
; #pragma unroll
;                 for (int m = mp; m < mp + 2; ++m) {
;                     const int row = row0 + ai * HALF + m * 16; const int tpos = row & (SEQ - 1);
;                     const u32x4 z4 = {0u, 0u, 0u, 0u};
;                     float f0[8], f1[8], f2[8], o[8];
;                     const bool edge = (ai == 0 && m == 0);
;                     unpack8((!edge || tpos >= 2) ? g0[m] : z4, f0); unpack8((!edge || tpos >= 1) ? g1[m] : z4, f1); unpack8(g2[m], f2);
;                     const float r = __builtin_amdgcn_rsqf(rs[m] * (1.f / DM) + EPS);
;                     const f32x4 v0 = acc[ai][bj][m][0] * r, v1 = acc[ai][bj][m][1] * r;
;                     const float uu[8] = {v0[0], v0[1], v0[2], v0[3], v1[0], v1[1], v1[2], v1[3]};
; #pragma unroll
;                     for (int e = 0; e < 8; ++e) { const float gc = b[e] + w0[e] * f0[e] + w1[e] * f1[e] + w2[e] * f2[e];
;                         const float sg = __builtin_amdgcn_rcpf(1.0f + __builtin_amdgcn_exp2f(-gc * 1.4426950408889634f));
;                         o[e] = gc * sg * uu[e]; }
;                     u32x4 w; w.x = cvt_pk_bf16(o[0], o[1]); w.y = cvt_pk_bf16(o[2], o[3]); w.z = cvt_pk_bf16(o[4], o[5]); w.w = cvt_pk_bf16(o[6], o[7]);
;                     *(u32x4*)(O + (size_t)row * DFF + col0) = w;
;                 }
	v_mul_f32_e32 v52, v88, v92
	v_fma_f32 v88, v82, v104, v86
	v_pk_mul_f32 v[96:97], v[56:57], v[96:97]
	v_and_b32_e32 v93, 0xffff0000, v93
	v_add_f32_e32 v88, v97, v88
	v_add_f32_e32 v96, v96, v88
	v_mul_f32_e32 v88, 0xbfb8aa3b, v96
	v_and_b32_e32 v92, 0xffff0000, v89
	v_exp_f32_e32 v97, v88
	v_fma_f32 v99, v83, v101, v87
	v_pk_mul_f32 v[88:89], v[78:79], v[92:93]
	v_mul_f32_e32 v92, v53, v52
	v_add_f32_e32 v89, v89, v99
	v_add_f32_e32 v88, v88, v89
	v_mul_f32_e32 v89, 0xbfb8aa3b, v88
	v_exp_f32_e32 v89, v89
	v_add_f32_e32 v52, 1.0, v97
	v_rcp_f32_e32 v93, v52
	v_lshlrev_b32_e32 v105, 16, v102
	v_add_f32_e32 v52, 1.0, v89
	v_rcp_f32_e32 v89, v52
	v_lshlrev_b32_e32 v53, 16, v94
	v_lshlrev_b32_e32 v52, 16, v90
	v_fma_f32 v97, v68, v105, v72
	v_pk_mul_f32 v[52:53], v[58:59], v[52:53]
	v_and_b32_e32 v102, 0xffff0000, v102
	v_add_f32_e32 v53, v53, v97
	v_add_f32_e32 v97, v52, v53
	v_mul_f32_e32 v52, 0xbfb8aa3b, v97
	v_exp_f32_e32 v52, v52
	v_mul_f32_e32 v53, v96, v93
	v_mul_f32_e32 v54, v54, v53
	v_mul_f32_e32 v88, v88, v89
	v_add_f32_e32 v52, 1.0, v52
	v_rcp_f32_e32 v89, v52
	v_and_b32_e32 v53, 0xffff0000, v94
	v_and_b32_e32 v52, 0xffff0000, v90
	v_fma_f32 v93, v69, v102, v73
	v_pk_mul_f32 v[52:53], v[64:65], v[52:53]
	v_mul_f32_e32 v55, v55, v88
	v_add_f32_e32 v53, v53, v93
	v_add_f32_e32 v90, v52, v53
	v_mul_f32_e32 v52, 0xbfb8aa3b, v90
	v_exp_f32_e32 v52, v52
	v_mul_f32_e32 v53, v97, v89
	v_mul_f32_e32 v88, v48, v53
	v_lshlrev_b32_e32 v53, 16, v95
	v_add_f32_e32 v48, 1.0, v52
	v_lshlrev_b32_e32 v52, 16, v91
	v_fma_f32 v89, v70, v106, v74
	v_pk_mul_f32 v[52:53], v[62:63], v[52:53]
	v_and_b32_e32 v103, 0xffff0000, v103
	v_add_f32_e32 v53, v53, v89
	v_add_f32_e32 v89, v52, v53
	v_mul_f32_e32 v52, 0xbfb8aa3b, v89
	v_exp_f32_e32 v93, v52
	v_and_b32_e32 v53, 0xffff0000, v95
	v_and_b32_e32 v52, 0xffff0000, v91
	v_fma_f32 v94, v71, v103, v75
	v_pk_mul_f32 v[52:53], v[66:67], v[52:53]
	v_rcp_f32_e32 v48, v48
	v_add_f32_e32 v53, v53, v94
	v_add_f32_e32 v52, v52, v53
	v_mul_f32_e32 v53, 0xbfb8aa3b, v52
	v_exp_f32_e32 v53, v53
	v_mul_f32_e32 v48, v90, v48
	v_add_f32_e32 v90, 1.0, v93
	v_rcp_f32_e32 v90, v90
	v_add_f32_e32 v53, 1.0, v53
	v_rcp_f32_e32 v53, v53
	v_mul_f32_e32 v91, v49, v48
	v_mul_f32_e32 v48, v89, v90
	v_mul_f32_e32 v89, v50, v48
	v_mul_f32_e32 v48, v52, v53
	v_mul_f32_e32 v51, v51, v48
	v_cvt_pk_bf16_f32 v48, v98, v92
	v_cvt_pk_bf16_f32 v49, v54, v55
	v_cvt_pk_bf16_f32 v50, v88, v91
	v_cvt_pk_bf16_f32 v51, v89, v51
	global_store_dwordx4 v[148:149], v[48:51], off offset:256 nt
	v_mad_i64_i32 v[88:89], s[0:1], v140, s60, 0
	s_nop 0
	v_lshl_add_u64 v[48:49], s[18:19], 0, v[128:129]
	v_lshl_add_u64 v[48:49], v[48:49], 0, v[126:127]
	v_add_co_u32_e32 v50, vcc, s62, v48
	s_nop 1
	v_addc_co_u32_e32 v51, vcc, -1, v49, vcc
	global_load_dwordx4 v[90:93], v[50:51], off offset:-2048 nt
	global_load_dword v106, v[150:151], off
	v_add_co_u32_e32 v50, vcc, s61, v48
	s_waitcnt vmcnt(1)
	v_lshlrev_b32_e32 v108, 16, v90
	v_addc_co_u32_e32 v51, vcc, -1, v49, vcc
	global_load_dwordx4 v[94:97], v[50:51], off offset:-3072 nt
	global_load_dwordx4 v[98:101], v[48:49], off nt
	v_mad_i64_i32 v[48:49], s[0:1], v152, s60, 0
	v_lshl_add_u64 v[48:49], s[18:19], 0, v[48:49]
	v_lshl_add_u64 v[102:103], v[48:49], 0, v[126:127]
	v_add_co_u32_e32 v52, vcc, s61, v102
	v_and_b32_e32 v109, 0xffff0000, v90
	s_nop 0
	v_addc_co_u32_e32 v53, vcc, -1, v103, vcc
	global_load_dwordx4 v[48:51], v[102:103], off nt
	s_nop 0
	global_load_dwordx4 v[52:55], v[52:53], off offset:-3072 nt
	v_add_co_u32_e32 v102, vcc, s62, v102
	s_waitcnt vmcnt(4)
	v_fmamk_f32 v90, v106, 0x3a000000, v229
	v_addc_co_u32_e32 v103, vcc, -1, v103, vcc
	global_load_dwordx4 v[102:105], v[102:103], off offset:-2048 nt
	s_nop 0
	global_load_dword v107, v[154:155], off
	v_rsq_f32_e32 v90, v90
	v_lshlrev_b32_e32 v112, 16, v92
	v_and_b32_e32 v106, 0xffff0000, v92
	v_lshlrev_b32_e32 v113, 16, v93
	v_and_b32_e32 v114, 0xffff0000, v93
	v_lshlrev_b32_e32 v110, 16, v91
	v_and_b32_e32 v111, 0xffff0000, v91
	v_pk_mul_f32 v[46:47], v[46:47], v[90:91] op_sel_hi:[1,0]
	v_pk_mul_f32 v[44:45], v[44:45], v[90:91] op_sel_hi:[1,0]
	v_fma_f32 v91, v80, v108, v84
	v_fma_f32 v109, v81, v109, v85
	s_waitcnt vmcnt(5)
	v_lshlrev_b32_e32 v93, 16, v94
	s_waitcnt vmcnt(4)
; __device__ __forceinline__ unsigned cvt_pk_bf16(float lo, float hi) { unsigned r; asm volatile("v_cvt_pk_bf16_f32 %0, %1, %2" : "=v"(r) : "v"(lo), "v"(hi)); return r; }
;     __device__ __forceinline__ void operator()(const f32x4 (&acc)[2][2][4][2], const Unit& u, int wr, int wc, int fr, int fq) const {
;     ...
;                 for (int m = mp; m < mp + 2; ++m) {
;                     const int row = row0 + ai * HALF + m * 16; const int tpos = row & (SEQ - 1);
;                     const u32x4 z4 = {0u, 0u, 0u, 0u};
;                     float f0[8], f1[8], f2[8], o[8];
;                     const bool edge = (ai == 0 && m == 0);
;                     unpack8((!edge || tpos >= 2) ? g0[m] : z4, f0); unpack8((!edge || tpos >= 1) ? g1[m] : z4, f1); unpack8(g2[m], f2);
;                     const float r = __builtin_amdgcn_rsqf(rs[m] * (1.f / DM) + EPS);
;                     const f32x4 v0 = acc[ai][bj][m][0] * r, v1 = acc[ai][bj][m][1] * r;
;                     const float uu[8] = {v0[0], v0[1], v0[2], v0[3], v1[0], v1[1], v1[2], v1[3]};
; #pragma unroll
;                     for (int e = 0; e < 8; ++e) { const float gc = b[e] + w0[e] * f0[e] + w1[e] * f1[e] + w2[e] * f2[e];
;                         const float sg = __builtin_amdgcn_rcpf(1.0f + __builtin_amdgcn_exp2f(-gc * 1.4426950408889634f));
;                         o[e] = gc * sg * uu[e]; }
;                     u32x4 w; w.x = cvt_pk_bf16(o[0], o[1]); w.y = cvt_pk_bf16(o[2], o[3]); w.z = cvt_pk_bf16(o[4], o[5]); w.w = cvt_pk_bf16(o[6], o[7]);
;                     *(u32x4*)(O + (size_t)row * DFF + col0) = w;
;                 }
	v_lshlrev_b32_e32 v92, 16, v98
	v_pk_mul_f32 v[92:93], v[60:61], v[92:93]
	s_nop 0
	v_add_f32_e32 v91, v93, v91
	v_add_f32_e32 v91, v92, v91
	v_mul_f32_e32 v92, 0xbfb8aa3b, v91
	v_exp_f32_e32 v108, v92
	v_and_b32_e32 v93, 0xffff0000, v94
	v_and_b32_e32 v92, 0xffff0000, v98
	v_pk_mul_f32 v[92:93], v[76:77], v[92:93]
	v_add_f32_e32 v94, 1.0, v108
	v_add_f32_e32 v93, v93, v109
	v_add_f32_e32 v92, v92, v93
	v_mul_f32_e32 v93, 0xbfb8aa3b, v92
	v_exp_f32_e32 v93, v93
	v_rcp_f32_e32 v94, v94
	v_pk_mul_f32 v[42:43], v[42:43], v[90:91] op_sel_hi:[1,0]
	v_pk_mul_f32 v[40:41], v[40:41], v[90:91] op_sel_hi:[1,0]
	v_add_f32_e32 v93, 1.0, v93
	v_rcp_f32_e32 v93, v93
	v_mul_f32_e32 v90, v91, v94
	v_mul_f32_e32 v94, v44, v90
	v_lshlrev_b32_e32 v91, 16, v95
	v_lshlrev_b32_e32 v90, 16, v99
	v_mul_f32_e32 v44, v92, v93
	v_fma_f32 v92, v82, v110, v86
	v_pk_mul_f32 v[90:91], v[56:57], v[90:91]
	v_fma_f32 v98, v83, v111, v87
	v_add_f32_e32 v91, v91, v92
	v_add_f32_e32 v92, v90, v91
	v_mul_f32_e32 v90, 0xbfb8aa3b, v92
	v_exp_f32_e32 v93, v90
	v_and_b32_e32 v91, 0xffff0000, v95
	v_and_b32_e32 v90, 0xffff0000, v99
	v_pk_mul_f32 v[90:91], v[78:79], v[90:91]
	v_mul_f32_e32 v95, v45, v44
	v_add_f32_e32 v91, v91, v98
	v_add_f32_e32 v90, v90, v91
	v_mul_f32_e32 v91, 0xbfb8aa3b, v90
	v_exp_f32_e32 v91, v91
	v_add_f32_e32 v44, 1.0, v93
	v_rcp_f32_e32 v93, v44
	v_lshlrev_b32_e32 v45, 16, v96
	v_add_f32_e32 v44, 1.0, v91
	v_rcp_f32_e32 v91, v44
	v_lshlrev_b32_e32 v44, 16, v100
	v_fma_f32 v98, v68, v112, v72
	v_pk_mul_f32 v[44:45], v[58:59], v[44:45]
	v_mul_f32_e32 v90, v90, v91
	v_add_f32_e32 v45, v45, v98
	v_add_f32_e32 v98, v44, v45
	v_mul_f32_e32 v44, 0xbfb8aa3b, v98
	v_exp_f32_e32 v44, v44
	v_mul_f32_e32 v45, v92, v93
	v_mul_f32_e32 v46, v46, v45
	v_and_b32_e32 v45, 0xffff0000, v96
	v_add_f32_e32 v44, 1.0, v44
	v_rcp_f32_e32 v91, v44
	v_and_b32_e32 v44, 0xffff0000, v100
	v_fma_f32 v92, v69, v106, v73
	v_pk_mul_f32 v[44:45], v[64:65], v[44:45]
	v_mul_f32_e32 v47, v47, v90
	v_add_f32_e32 v45, v45, v92
	v_add_f32_e32 v92, v44, v45
	v_mul_f32_e32 v44, 0xbfb8aa3b, v92
	v_exp_f32_e32 v44, v44
	v_mul_f32_e32 v45, v98, v91
	v_mul_f32_e32 v90, v40, v45
	v_lshlrev_b32_e32 v45, 16, v97
	v_add_f32_e32 v40, 1.0, v44
	v_lshlrev_b32_e32 v44, 16, v101
	v_fma_f32 v91, v70, v113, v74
	v_pk_mul_f32 v[44:45], v[62:63], v[44:45]
	v_fma_f32 v96, v71, v114, v75
	v_add_f32_e32 v45, v45, v91
	v_add_f32_e32 v91, v44, v45
	v_mul_f32_e32 v44, 0xbfb8aa3b, v91
	v_exp_f32_e32 v93, v44
	v_and_b32_e32 v45, 0xffff0000, v97
	v_and_b32_e32 v44, 0xffff0000, v101
	v_pk_mul_f32 v[44:45], v[66:67], v[44:45]
	v_rcp_f32_e32 v40, v40
	v_add_f32_e32 v45, v45, v96
	v_add_f32_e32 v44, v44, v45
	v_mul_f32_e32 v45, 0xbfb8aa3b, v44
	v_exp_f32_e32 v45, v45
	v_mul_f32_e32 v40, v92, v40
	v_add_f32_e32 v92, 1.0, v93
	v_rcp_f32_e32 v92, v92
	v_add_f32_e32 v45, 1.0, v45
	v_rcp_f32_e32 v45, v45
	v_mul_f32_e32 v93, v41, v40
	v_mul_f32_e32 v40, v91, v92
	v_mul_f32_e32 v91, v42, v40
	v_mul_f32_e32 v40, v44, v45
	v_mul_f32_e32 v43, v43, v40
	v_cvt_pk_bf16_f32 v40, v94, v95
	v_cvt_pk_bf16_f32 v41, v46, v47
	v_cvt_pk_bf16_f32 v42, v90, v93
	v_cvt_pk_bf16_f32 v43, v91, v43
	global_store_dwordx4 v[130:131], v[40:43], off offset:256 nt
	s_waitcnt vmcnt(2)
	v_and_b32_e32 v44, 0xffff0000, v102
	v_fma_f32 v44, v81, v44, v85
	s_waitcnt vmcnt(1)
	v_fmamk_f32 v40, v107, 0x3a000000, v229
	v_rsq_f32_e32 v40, v40
	v_lshlrev_b32_e32 v41, 16, v102
	v_lshlrev_b32_e32 v43, 16, v52
	v_lshlrev_b32_e32 v42, 16, v48
	v_pk_mul_f32 v[38:39], v[38:39], v[40:41] op_sel_hi:[1,0]
	v_pk_mul_f32 v[36:37], v[36:37], v[40:41] op_sel_hi:[1,0]
	v_fma_f32 v41, v80, v41, v84
	v_pk_mul_f32 v[42:43], v[60:61], v[42:43]
	v_lshlrev_b32_e32 v45, 16, v103
	v_add_f32_e32 v41, v43, v41
	v_add_f32_e32 v41, v42, v41
	v_mul_f32_e32 v42, 0xbfb8aa3b, v41
	v_exp_f32_e32 v93, v42
	v_and_b32_e32 v43, 0xffff0000, v52
	v_and_b32_e32 v42, 0xffff0000, v48
	v_pk_mul_f32 v[42:43], v[76:77], v[42:43]
	v_pk_mul_f32 v[34:35], v[34:35], v[40:41] op_sel_hi:[1,0]
	v_add_f32_e32 v43, v43, v44
	v_add_f32_e32 v42, v42, v43
	v_mul_f32_e32 v43, 0xbfb8aa3b, v42
	v_exp_f32_e32 v43, v43
	v_add_f32_e32 v44, 1.0, v93
	v_rcp_f32_e32 v44, v44
	v_pk_mul_f32 v[32:33], v[32:33], v[40:41] op_sel_hi:[1,0]
	v_add_f32_e32 v43, 1.0, v43
	v_rcp_f32_e32 v43, v43
	v_mul_f32_e32 v40, v41, v44
	v_mul_f32_e32 v44, v36, v40
	v_lshlrev_b32_e32 v41, 16, v53
	v_lshlrev_b32_e32 v40, 16, v49
	v_mul_f32_e32 v36, v42, v43
	v_fma_f32 v42, v82, v45, v86
	v_pk_mul_f32 v[40:41], v[56:57], v[40:41]
	v_and_b32_e32 v46, 0xffff0000, v103
	v_add_f32_e32 v41, v41, v42
	v_add_f32_e32 v42, v40, v41
	v_mul_f32_e32 v40, 0xbfb8aa3b, v42
	v_exp_f32_e32 v43, v40
	v_and_b32_e32 v41, 0xffff0000, v53
	v_and_b32_e32 v40, 0xffff0000, v49
	v_fma_f32 v45, v83, v46, v87
	v_pk_mul_f32 v[40:41], v[78:79], v[40:41]
	v_lshlrev_b32_e32 v47, 16, v104
	v_add_f32_e32 v41, v41, v45
	v_add_f32_e32 v40, v40, v41
	v_mul_f32_e32 v41, 0xbfb8aa3b, v40
	v_exp_f32_e32 v41, v41
	v_mul_f32_e32 v45, v37, v36
	v_add_f32_e32 v36, 1.0, v43
	v_rcp_f32_e32 v43, v36
	v_add_f32_e32 v36, 1.0, v41
	v_rcp_f32_e32 v41, v36
	v_lshlrev_b32_e32 v37, 16, v54
	v_lshlrev_b32_e32 v36, 16, v50
	v_fma_f32 v46, v68, v47, v72
	v_pk_mul_f32 v[36:37], v[58:59], v[36:37]
	v_and_b32_e32 v90, 0xffff0000, v104
	v_add_f32_e32 v37, v37, v46
	v_add_f32_e32 v46, v36, v37
	v_mul_f32_e32 v36, 0xbfb8aa3b, v46
	v_exp_f32_e32 v36, v36
	v_mul_f32_e32 v37, v42, v43
	v_mul_f32_e32 v38, v38, v37
	v_mul_f32_e32 v40, v40, v41
	v_add_f32_e32 v36, 1.0, v36
	v_rcp_f32_e32 v41, v36
	v_and_b32_e32 v37, 0xffff0000, v54
	v_and_b32_e32 v36, 0xffff0000, v50
	v_fma_f32 v42, v69, v90, v73
	v_pk_mul_f32 v[36:37], v[64:65], v[36:37]
; __device__ __forceinline__ unsigned cvt_pk_bf16(float lo, float hi) { unsigned r; asm volatile("v_cvt_pk_bf16_f32 %0, %1, %2" : "=v"(r) : "v"(lo), "v"(hi)); return r; }
;     __device__ __forceinline__ void operator()(const f32x4 (&acc)[2][2][4][2], const Unit& u, int wr, int wc, int fr, int fq) const {
;     ...
;                 for (int m = mp; m < mp + 2; ++m) {
;                     const int row = row0 + ai * HALF + m * 16; const int tpos = row & (SEQ - 1);
;                     const bf16_t* gp = G + (size_t)row * DFF + col0;
;                     g2[m] = *(const u32x4*)gp;
;                     const bool edge = (ai == 0 && m == 0);
;                     g1[m] = *(const u32x4*)(gp - ((!edge || tpos >= 1) ? DFF : 0));
;                     g0[m] = *(const u32x4*)(gp - ((!edge || tpos >= 2) ? 2 * DFF : 0));
;                     rs[m] = ss[row];
;                 }
; #pragma unroll
;                 for (int m = mp; m < mp + 2; ++m) {
;                     const int row = row0 + ai * HALF + m * 16; const int tpos = row & (SEQ - 1);
;                     const u32x4 z4 = {0u, 0u, 0u, 0u};
;                     float f0[8], f1[8], f2[8], o[8];
;                     const bool edge = (ai == 0 && m == 0);
;                     unpack8((!edge || tpos >= 2) ? g0[m] : z4, f0); unpack8((!edge || tpos >= 1) ? g1[m] : z4, f1); unpack8(g2[m], f2);
;                     const float r = __builtin_amdgcn_rsqf(rs[m] * (1.f / DM) + EPS);
;                     const f32x4 v0 = acc[ai][bj][m][0] * r, v1 = acc[ai][bj][m][1] * r;
;                     const float uu[8] = {v0[0], v0[1], v0[2], v0[3], v1[0], v1[1], v1[2], v1[3]};
; #pragma unroll
;                     for (int e = 0; e < 8; ++e) { const float gc = b[e] + w0[e] * f0[e] + w1[e] * f1[e] + w2[e] * f2[e];
;                         const float sg = __builtin_amdgcn_rcpf(1.0f + __builtin_amdgcn_exp2f(-gc * 1.4426950408889634f));
;                         o[e] = gc * sg * uu[e]; }
;                     u32x4 w; w.x = cvt_pk_bf16(o[0], o[1]); w.y = cvt_pk_bf16(o[2], o[3]); w.z = cvt_pk_bf16(o[4], o[5]); w.w = cvt_pk_bf16(o[6], o[7]);
;                     *(u32x4*)(O + (size_t)row * DFF + col0) = w;
;                 }
	v_lshlrev_b32_e32 v91, 16, v105
	v_add_f32_e32 v37, v37, v42
	v_add_f32_e32 v42, v36, v37
	v_mul_f32_e32 v36, 0xbfb8aa3b, v42
	v_exp_f32_e32 v36, v36
	v_mul_f32_e32 v37, v46, v41
	v_mul_f32_e32 v39, v39, v40
	v_mul_f32_e32 v40, v32, v37
	v_add_f32_e32 v32, 1.0, v36
	v_lshlrev_b32_e32 v37, 16, v55
	v_lshlrev_b32_e32 v36, 16, v51
	v_fma_f32 v41, v70, v91, v74
	v_pk_mul_f32 v[36:37], v[62:63], v[36:37]
	v_and_b32_e32 v92, 0xffff0000, v105
	v_add_f32_e32 v37, v37, v41
	v_add_f32_e32 v41, v36, v37
	v_mul_f32_e32 v36, 0xbfb8aa3b, v41
	v_exp_f32_e32 v43, v36
	v_and_b32_e32 v37, 0xffff0000, v55
	v_and_b32_e32 v36, 0xffff0000, v51
	v_fma_f32 v46, v71, v92, v75
	v_pk_mul_f32 v[36:37], v[66:67], v[36:37]
	v_rcp_f32_e32 v32, v32
	v_add_f32_e32 v37, v37, v46
	v_add_f32_e32 v36, v36, v37
	v_mul_f32_e32 v37, 0xbfb8aa3b, v36
	v_exp_f32_e32 v37, v37
	v_mul_f32_e32 v32, v42, v32
	v_add_f32_e32 v42, 1.0, v43
	v_rcp_f32_e32 v42, v42
	v_add_f32_e32 v37, 1.0, v37
	v_rcp_f32_e32 v37, v37
	v_mul_f32_e32 v43, v33, v32
	v_mul_f32_e32 v32, v41, v42
	v_mul_f32_e32 v41, v34, v32
	v_mul_f32_e32 v32, v36, v37
	v_mul_f32_e32 v35, v35, v32
	v_cvt_pk_bf16_f32 v32, v44, v45
	v_cvt_pk_bf16_f32 v33, v38, v39
	v_cvt_pk_bf16_f32 v34, v40, v43
	v_cvt_pk_bf16_f32 v35, v41, v35
	global_store_dwordx4 v[132:133], v[32:35], off offset:256 nt
	v_mad_i64_i32 v[40:41], s[0:1], v141, s60, 0
	s_nop 0
	v_lshl_add_u64 v[32:33], s[18:19], 0, v[88:89]
	v_lshl_add_u64 v[32:33], v[32:33], 0, v[126:127]
	v_add_co_u32_e32 v34, vcc, s62, v32
	s_nop 1
	v_addc_co_u32_e32 v35, vcc, -1, v33, vcc
	global_load_dwordx4 v[42:45], v[34:35], off offset:-2048 nt
	global_load_dword v92, v[202:203], off offset:512
	v_add_co_u32_e32 v34, vcc, s61, v32
	s_waitcnt vmcnt(1)
	v_and_b32_e32 v93, 0xffff0000, v42
	v_addc_co_u32_e32 v35, vcc, -1, v33, vcc
	global_load_dwordx4 v[46:49], v[34:35], off offset:-3072 nt
	global_load_dwordx4 v[50:53], v[32:33], off nt
	v_mad_i64_i32 v[32:33], s[0:1], v138, s60, 0
	v_lshl_add_u64 v[32:33], s[18:19], 0, v[32:33]
	v_lshl_add_u64 v[54:55], v[32:33], 0, v[126:127]
	v_add_co_u32_e32 v36, vcc, s61, v54
	v_lshlrev_b32_e32 v96, 16, v44
	s_nop 0
	v_addc_co_u32_e32 v37, vcc, -1, v55, vcc
	global_load_dwordx4 v[32:35], v[54:55], off nt
	s_nop 0
	global_load_dwordx4 v[36:39], v[36:37], off offset:-3072 nt
	v_add_co_u32_e32 v54, vcc, s62, v54
	v_lshlrev_b32_e32 v97, 16, v45
	s_nop 0
	v_addc_co_u32_e32 v55, vcc, -1, v55, vcc
	global_load_dwordx4 v[88:91], v[54:55], off offset:-2048 nt
	s_nop 0
	global_load_dword v54, v[202:203], off offset:576
	v_lshlrev_b32_e32 v55, 16, v42
	s_waitcnt vmcnt(6)
	v_fmamk_f32 v42, v92, 0x3a000000, v229
	v_rsq_f32_e32 v42, v42
	v_and_b32_e32 v92, 0xffff0000, v44
	v_and_b32_e32 v98, 0xffff0000, v45
	v_lshlrev_b32_e32 v94, 16, v43
	v_and_b32_e32 v95, 0xffff0000, v43
	v_pk_mul_f32 v[30:31], v[30:31], v[42:43] op_sel_hi:[1,0]
	v_pk_mul_f32 v[28:29], v[28:29], v[42:43] op_sel_hi:[1,0]
	v_fma_f32 v43, v80, v55, v84
	v_fma_f32 v93, v81, v93, v85
	s_waitcnt vmcnt(5)
	v_lshlrev_b32_e32 v45, 16, v46
	s_waitcnt vmcnt(4)
	v_lshlrev_b32_e32 v44, 16, v50
	v_pk_mul_f32 v[44:45], v[60:61], v[44:45]
	s_nop 0
	v_add_f32_e32 v43, v45, v43
	v_add_f32_e32 v43, v44, v43
	v_mul_f32_e32 v44, 0xbfb8aa3b, v43
	v_exp_f32_e32 v55, v44
	v_and_b32_e32 v45, 0xffff0000, v46
	v_and_b32_e32 v44, 0xffff0000, v50
	v_pk_mul_f32 v[44:45], v[76:77], v[44:45]
	v_add_f32_e32 v46, 1.0, v55
	v_add_f32_e32 v45, v45, v93
	v_add_f32_e32 v44, v44, v45
	v_mul_f32_e32 v45, 0xbfb8aa3b, v44
	v_exp_f32_e32 v45, v45
	v_rcp_f32_e32 v46, v46
	v_pk_mul_f32 v[26:27], v[26:27], v[42:43] op_sel_hi:[1,0]
	v_pk_mul_f32 v[24:25], v[24:25], v[42:43] op_sel_hi:[1,0]
	v_add_f32_e32 v45, 1.0, v45
	v_rcp_f32_e32 v45, v45
	v_mul_f32_e32 v42, v43, v46
	v_mul_f32_e32 v46, v28, v42
	v_lshlrev_b32_e32 v43, 16, v47
	v_lshlrev_b32_e32 v42, 16, v51
	v_mul_f32_e32 v28, v44, v45
	v_fma_f32 v44, v82, v94, v86
	v_pk_mul_f32 v[42:43], v[56:57], v[42:43]
	v_fma_f32 v50, v83, v95, v87
	v_add_f32_e32 v43, v43, v44
	v_add_f32_e32 v44, v42, v43
	v_mul_f32_e32 v42, 0xbfb8aa3b, v44
	v_exp_f32_e32 v45, v42
	v_and_b32_e32 v43, 0xffff0000, v47
	v_and_b32_e32 v42, 0xffff0000, v51
	v_pk_mul_f32 v[42:43], v[78:79], v[42:43]
	v_mul_f32_e32 v47, v29, v28
	v_add_f32_e32 v43, v43, v50
	v_add_f32_e32 v42, v42, v43
	v_mul_f32_e32 v43, 0xbfb8aa3b, v42
	v_exp_f32_e32 v43, v43
	v_add_f32_e32 v28, 1.0, v45
	v_rcp_f32_e32 v45, v28
	v_lshlrev_b32_e32 v29, 16, v48
	v_add_f32_e32 v28, 1.0, v43
	v_rcp_f32_e32 v43, v28
	v_lshlrev_b32_e32 v28, 16, v52
	v_fma_f32 v50, v68, v96, v72
	v_pk_mul_f32 v[28:29], v[58:59], v[28:29]
	v_mul_f32_e32 v42, v42, v43
	v_add_f32_e32 v29, v29, v50
	v_add_f32_e32 v50, v28, v29
	v_mul_f32_e32 v28, 0xbfb8aa3b, v50
	v_exp_f32_e32 v28, v28
	v_mul_f32_e32 v29, v44, v45
	v_mul_f32_e32 v30, v30, v29
	v_and_b32_e32 v29, 0xffff0000, v48
	v_add_f32_e32 v28, 1.0, v28
	v_rcp_f32_e32 v43, v28
	v_and_b32_e32 v28, 0xffff0000, v52
	v_fma_f32 v44, v69, v92, v73
	v_pk_mul_f32 v[28:29], v[64:65], v[28:29]
	v_mul_f32_e32 v31, v31, v42
	v_add_f32_e32 v29, v29, v44
	v_add_f32_e32 v44, v28, v29
	v_mul_f32_e32 v28, 0xbfb8aa3b, v44
	v_exp_f32_e32 v28, v28
	v_mul_f32_e32 v29, v50, v43
	v_mul_f32_e32 v42, v24, v29
	v_lshlrev_b32_e32 v29, 16, v49
	v_add_f32_e32 v24, 1.0, v28
	v_lshlrev_b32_e32 v28, 16, v53
	v_fma_f32 v43, v70, v97, v74
	v_pk_mul_f32 v[28:29], v[62:63], v[28:29]
	v_fma_f32 v48, v71, v98, v75
	v_add_f32_e32 v29, v29, v43
	v_add_f32_e32 v43, v28, v29
	v_mul_f32_e32 v28, 0xbfb8aa3b, v43
	v_exp_f32_e32 v45, v28
	v_and_b32_e32 v29, 0xffff0000, v49
	v_and_b32_e32 v28, 0xffff0000, v53
	v_pk_mul_f32 v[28:29], v[66:67], v[28:29]
	v_rcp_f32_e32 v24, v24
	v_add_f32_e32 v29, v29, v48
	v_add_f32_e32 v28, v28, v29
	v_mul_f32_e32 v29, 0xbfb8aa3b, v28
	v_exp_f32_e32 v29, v29
	v_mul_f32_e32 v24, v44, v24
	v_add_f32_e32 v44, 1.0, v45
	v_rcp_f32_e32 v44, v44
	v_add_f32_e32 v29, 1.0, v29
	v_rcp_f32_e32 v29, v29
	v_mul_f32_e32 v45, v25, v24
	v_mul_f32_e32 v24, v43, v44
	v_mul_f32_e32 v43, v26, v24
	v_mul_f32_e32 v24, v28, v29
	v_mul_f32_e32 v27, v27, v24
	v_cvt_pk_bf16_f32 v24, v46, v47
	v_cvt_pk_bf16_f32 v25, v30, v31
	v_cvt_pk_bf16_f32 v26, v42, v45
	v_cvt_pk_bf16_f32 v27, v43, v27
	global_store_dwordx4 v[134:135], v[24:27], off offset:256 nt
	s_waitcnt vmcnt(2)
; __device__ __forceinline__ unsigned cvt_pk_bf16(float lo, float hi) { unsigned r; asm volatile("v_cvt_pk_bf16_f32 %0, %1, %2" : "=v"(r) : "v"(lo), "v"(hi)); return r; }
;     __device__ __forceinline__ void operator()(const f32x4 (&acc)[2][2][4][2], const Unit& u, int wr, int wc, int fr, int fq) const {
;     ...
;                 for (int m = mp; m < mp + 2; ++m) {
;                     const int row = row0 + ai * HALF + m * 16; const int tpos = row & (SEQ - 1);
;                     const bf16_t* gp = G + (size_t)row * DFF + col0;
;                     g2[m] = *(const u32x4*)gp;
;                     const bool edge = (ai == 0 && m == 0);
;                     g1[m] = *(const u32x4*)(gp - ((!edge || tpos >= 1) ? DFF : 0));
;                     g0[m] = *(const u32x4*)(gp - ((!edge || tpos >= 2) ? 2 * DFF : 0));
;                     rs[m] = ss[row];
;                 }
; #pragma unroll
;                 for (int m = mp; m < mp + 2; ++m) {
;                     const int row = row0 + ai * HALF + m * 16; const int tpos = row & (SEQ - 1);
;                     const u32x4 z4 = {0u, 0u, 0u, 0u};
;                     float f0[8], f1[8], f2[8], o[8];
;                     const bool edge = (ai == 0 && m == 0);
;                     unpack8((!edge || tpos >= 2) ? g0[m] : z4, f0); unpack8((!edge || tpos >= 1) ? g1[m] : z4, f1); unpack8(g2[m], f2);
;                     const float r = __builtin_amdgcn_rsqf(rs[m] * (1.f / DM) + EPS);
;                     const f32x4 v0 = acc[ai][bj][m][0] * r, v1 = acc[ai][bj][m][1] * r;
;                     const float uu[8] = {v0[0], v0[1], v0[2], v0[3], v1[0], v1[1], v1[2], v1[3]};
; #pragma unroll
;                     for (int e = 0; e < 8; ++e) { const float gc = b[e] + w0[e] * f0[e] + w1[e] * f1[e] + w2[e] * f2[e];
;                         const float sg = __builtin_amdgcn_rcpf(1.0f + __builtin_amdgcn_exp2f(-gc * 1.4426950408889634f));
;                         o[e] = gc * sg * uu[e]; }
;                     u32x4 w; w.x = cvt_pk_bf16(o[0], o[1]); w.y = cvt_pk_bf16(o[2], o[3]); w.z = cvt_pk_bf16(o[4], o[5]); w.w = cvt_pk_bf16(o[6], o[7]);
;                     *(u32x4*)(O + (size_t)row * DFF + col0) = w;
;                 }
	v_and_b32_e32 v28, 0xffff0000, v88
	v_fma_f32 v28, v81, v28, v85
	s_waitcnt vmcnt(1)
	v_fmamk_f32 v24, v54, 0x3a000000, v229
	v_rsq_f32_e32 v24, v24
	v_lshlrev_b32_e32 v25, 16, v88
	v_lshlrev_b32_e32 v27, 16, v36
	v_lshlrev_b32_e32 v26, 16, v32
	v_pk_mul_f32 v[22:23], v[22:23], v[24:25] op_sel_hi:[1,0]
	v_pk_mul_f32 v[20:21], v[20:21], v[24:25] op_sel_hi:[1,0]
	v_fma_f32 v25, v80, v25, v84
	v_pk_mul_f32 v[26:27], v[60:61], v[26:27]
	v_lshlrev_b32_e32 v29, 16, v89
	v_add_f32_e32 v25, v27, v25
	v_add_f32_e32 v25, v26, v25
	v_mul_f32_e32 v26, 0xbfb8aa3b, v25
	v_exp_f32_e32 v45, v26
	v_and_b32_e32 v27, 0xffff0000, v36
	v_and_b32_e32 v26, 0xffff0000, v32
	v_pk_mul_f32 v[26:27], v[76:77], v[26:27]
	v_pk_mul_f32 v[18:19], v[18:19], v[24:25] op_sel_hi:[1,0]
	v_add_f32_e32 v27, v27, v28
	v_add_f32_e32 v26, v26, v27
	v_mul_f32_e32 v27, 0xbfb8aa3b, v26
	v_exp_f32_e32 v27, v27
	v_add_f32_e32 v28, 1.0, v45
	v_rcp_f32_e32 v28, v28
	v_pk_mul_f32 v[16:17], v[16:17], v[24:25] op_sel_hi:[1,0]
	v_add_f32_e32 v27, 1.0, v27
	v_rcp_f32_e32 v27, v27
	v_mul_f32_e32 v24, v25, v28
	v_mul_f32_e32 v28, v20, v24
	v_lshlrev_b32_e32 v25, 16, v37
	v_lshlrev_b32_e32 v24, 16, v33
	v_mul_f32_e32 v20, v26, v27
	v_fma_f32 v26, v82, v29, v86
	v_pk_mul_f32 v[24:25], v[56:57], v[24:25]
	v_and_b32_e32 v30, 0xffff0000, v89
	v_add_f32_e32 v25, v25, v26
	v_add_f32_e32 v26, v24, v25
	v_mul_f32_e32 v24, 0xbfb8aa3b, v26
	v_exp_f32_e32 v27, v24
	v_and_b32_e32 v25, 0xffff0000, v37
	v_and_b32_e32 v24, 0xffff0000, v33
	v_fma_f32 v29, v83, v30, v87
	v_pk_mul_f32 v[24:25], v[78:79], v[24:25]
	v_lshlrev_b32_e32 v31, 16, v90
	v_add_f32_e32 v25, v25, v29
	v_add_f32_e32 v24, v24, v25
	v_mul_f32_e32 v25, 0xbfb8aa3b, v24
	v_exp_f32_e32 v25, v25
	v_mul_f32_e32 v29, v21, v20
	v_add_f32_e32 v20, 1.0, v27
	v_rcp_f32_e32 v27, v20
	v_add_f32_e32 v20, 1.0, v25
	v_rcp_f32_e32 v25, v20
	v_lshlrev_b32_e32 v21, 16, v38
	v_lshlrev_b32_e32 v20, 16, v34
	v_fma_f32 v30, v68, v31, v72
	v_pk_mul_f32 v[20:21], v[58:59], v[20:21]
	v_and_b32_e32 v42, 0xffff0000, v90
	v_add_f32_e32 v21, v21, v30
	v_add_f32_e32 v30, v20, v21
	v_mul_f32_e32 v20, 0xbfb8aa3b, v30
	v_exp_f32_e32 v20, v20
	v_mul_f32_e32 v21, v26, v27
	v_mul_f32_e32 v22, v22, v21
	v_mul_f32_e32 v24, v24, v25
	v_add_f32_e32 v20, 1.0, v20
	v_rcp_f32_e32 v25, v20
	v_and_b32_e32 v21, 0xffff0000, v38
	v_and_b32_e32 v20, 0xffff0000, v34
	v_fma_f32 v26, v69, v42, v73
	v_pk_mul_f32 v[20:21], v[64:65], v[20:21]
	v_lshlrev_b32_e32 v43, 16, v91
	v_add_f32_e32 v21, v21, v26
	v_add_f32_e32 v26, v20, v21
	v_mul_f32_e32 v20, 0xbfb8aa3b, v26
	v_exp_f32_e32 v20, v20
	v_mul_f32_e32 v21, v30, v25
	v_mul_f32_e32 v23, v23, v24
	v_mul_f32_e32 v24, v16, v21
	v_add_f32_e32 v16, 1.0, v20
	v_lshlrev_b32_e32 v21, 16, v39
	v_lshlrev_b32_e32 v20, 16, v35
	v_fma_f32 v25, v70, v43, v74
	v_pk_mul_f32 v[20:21], v[62:63], v[20:21]
	v_and_b32_e32 v44, 0xffff0000, v91
	v_add_f32_e32 v21, v21, v25
	v_add_f32_e32 v25, v20, v21
	v_mul_f32_e32 v20, 0xbfb8aa3b, v25
	v_exp_f32_e32 v27, v20
	v_and_b32_e32 v21, 0xffff0000, v39
	v_and_b32_e32 v20, 0xffff0000, v35
	v_fma_f32 v30, v71, v44, v75
	v_pk_mul_f32 v[20:21], v[66:67], v[20:21]
	v_rcp_f32_e32 v16, v16
	v_add_f32_e32 v21, v21, v30
	v_add_f32_e32 v20, v20, v21
	v_mul_f32_e32 v21, 0xbfb8aa3b, v20
	v_exp_f32_e32 v21, v21
	v_mul_f32_e32 v16, v26, v16
	v_add_f32_e32 v26, 1.0, v27
	v_rcp_f32_e32 v26, v26
	v_add_f32_e32 v21, 1.0, v21
	v_rcp_f32_e32 v21, v21
	v_mul_f32_e32 v27, v17, v16
	v_mul_f32_e32 v16, v25, v26
	v_mul_f32_e32 v25, v18, v16
	v_mul_f32_e32 v16, v20, v21
	v_mul_f32_e32 v19, v19, v16
	v_cvt_pk_bf16_f32 v16, v28, v29
	v_cvt_pk_bf16_f32 v17, v22, v23
	v_cvt_pk_bf16_f32 v18, v24, v27
	v_cvt_pk_bf16_f32 v19, v25, v19
	global_store_dwordx4 v[122:123], v[16:19], off offset:256 nt
	s_nop 1
	v_lshl_add_u64 v[16:17], s[18:19], 0, v[40:41]
	v_lshl_add_u64 v[16:17], v[16:17], 0, v[126:127]
	v_add_co_u32_e32 v18, vcc, s62, v16
	s_nop 1
	v_addc_co_u32_e32 v19, vcc, -1, v17, vcc
	global_load_dwordx4 v[24:27], v[18:19], off offset:-2048 nt
	global_load_dword v40, v[202:203], off offset:640
	v_add_co_u32_e32 v18, vcc, s61, v16
	s_waitcnt vmcnt(1)
	v_lshlrev_b32_e32 v42, 16, v24
	v_addc_co_u32_e32 v19, vcc, -1, v17, vcc
	global_load_dwordx4 v[28:31], v[18:19], off offset:-3072 nt
	global_load_dwordx4 v[32:35], v[16:17], off nt
	v_mad_i64_i32 v[16:17], s[0:1], v139, s60, 0
	v_lshl_add_u64 v[16:17], s[18:19], 0, v[16:17]
	v_lshl_add_u64 v[36:37], v[16:17], 0, v[126:127]
	v_add_co_u32_e32 v20, vcc, s61, v36
	v_and_b32_e32 v43, 0xffff0000, v24
	s_nop 0
	v_addc_co_u32_e32 v21, vcc, -1, v37, vcc
	global_load_dwordx4 v[16:19], v[36:37], off nt
	s_nop 0
	global_load_dwordx4 v[20:23], v[20:21], off offset:-3072 nt
	v_add_co_u32_e32 v36, vcc, s62, v36
	s_waitcnt vmcnt(4)
	v_fmamk_f32 v24, v40, 0x3a000000, v229
	v_addc_co_u32_e32 v37, vcc, -1, v37, vcc
	global_load_dwordx4 v[36:39], v[36:37], off offset:-2048 nt
	s_nop 0
	global_load_dword v41, v[202:203], off offset:704
	v_rsq_f32_e32 v24, v24
	v_lshlrev_b32_e32 v46, 16, v26
	v_and_b32_e32 v40, 0xffff0000, v26
	v_lshlrev_b32_e32 v47, 16, v27
	v_and_b32_e32 v48, 0xffff0000, v27
	v_lshlrev_b32_e32 v44, 16, v25
	v_and_b32_e32 v45, 0xffff0000, v25
	v_pk_mul_f32 v[14:15], v[14:15], v[24:25] op_sel_hi:[1,0]
	v_pk_mul_f32 v[12:13], v[12:13], v[24:25] op_sel_hi:[1,0]
	v_fma_f32 v25, v80, v42, v84
	v_fma_f32 v43, v81, v43, v85
	s_andn2_b64 vcc, exec, s[4:5]
	s_mov_b64 s[0:1], -1
	s_waitcnt vmcnt(5)
	v_lshlrev_b32_e32 v27, 16, v28
	s_waitcnt vmcnt(4)
; #define PG8_BAR __builtin_amdgcn_s_barrier()
;     __device__ __forceinline__ void operator()(const f32x4 (&acc)[2][2][4][2], const Unit& u, int wr, int wc, int fr, int fq) const {
;     ...
;                 for (int m = mp; m < mp + 2; ++m) {
;                     const int row = row0 + ai * HALF + m * 16; const int tpos = row & (SEQ - 1);
;                     const u32x4 z4 = {0u, 0u, 0u, 0u};
;                     float f0[8], f1[8], f2[8], o[8];
;                     const bool edge = (ai == 0 && m == 0);
;                     unpack8((!edge || tpos >= 2) ? g0[m] : z4, f0); unpack8((!edge || tpos >= 1) ? g1[m] : z4, f1); unpack8(g2[m], f2);
;                     const float r = __builtin_amdgcn_rsqf(rs[m] * (1.f / DM) + EPS);
;                     const f32x4 v0 = acc[ai][bj][m][0] * r, v1 = acc[ai][bj][m][1] * r;
;                     const float uu[8] = {v0[0], v0[1], v0[2], v0[3], v1[0], v1[1], v1[2], v1[3]};
; #pragma unroll
;                     for (int e = 0; e < 8; ++e) { const float gc = b[e] + w0[e] * f0[e] + w1[e] * f1[e] + w2[e] * f2[e];
;                         const float sg = __builtin_amdgcn_rcpf(1.0f + __builtin_amdgcn_exp2f(-gc * 1.4426950408889634f));
;                         o[e] = gc * sg * uu[e]; }
;                     u32x4 w; w.x = cvt_pk_bf16(o[0], o[1]); w.y = cvt_pk_bf16(o[2], o[3]); w.z = cvt_pk_bf16(o[4], o[5]); w.w = cvt_pk_bf16(o[6], o[7]);
;                     *(u32x4*)(O + (size_t)row * DFF + col0) = w;
;                 }
; template <class Epi, class Sched, bool SP2 = PG8_SP2>
; __device__ __forceinline__ void gemm_phase(LAS unsigned char* lds, const Gemm g, const Sched& S, const Epi& E) {
;     ...
;         if (wr == 0) PG8_BAR;
;         E(acc, cur, wr, wc, fr, fq);
;         if constexpr (Epi::POST) { asm volatile("s_waitcnt vmcnt(0)" ::: "memory"); PG8_BAR; asm volatile("" ::: "memory"); E.post(cur, tid); }
;         if (!has_next) break;
; #pragma unroll
;         for (int a = 0; a < 2; ++a)
; #pragma unroll
;             for (int b = 0; b < 2; ++b)
; #pragma unroll
;                 for (int m = 0; m < 4; ++m)
; #pragma unroll
;                     for (int n = 0; n < 2; ++n) acc[a][b][m][n] = (f32x4){0.f, 0.f, 0.f, 0.f};
;         cur = nxt; cA = nA; cB = nB; ++ui;
;         if (wr == 1) PG8_BAR;
;     }
	v_lshlrev_b32_e32 v26, 16, v32
	v_pk_mul_f32 v[26:27], v[60:61], v[26:27]
	s_nop 0
	v_add_f32_e32 v25, v27, v25
	v_add_f32_e32 v25, v26, v25
	v_mul_f32_e32 v26, 0xbfb8aa3b, v25
	v_exp_f32_e32 v42, v26
	v_and_b32_e32 v27, 0xffff0000, v28
	v_and_b32_e32 v26, 0xffff0000, v32
	v_pk_mul_f32 v[26:27], v[76:77], v[26:27]
	v_add_f32_e32 v28, 1.0, v42
	v_add_f32_e32 v27, v27, v43
	v_add_f32_e32 v26, v26, v27
	v_mul_f32_e32 v27, 0xbfb8aa3b, v26
	v_exp_f32_e32 v27, v27
	v_rcp_f32_e32 v28, v28
	v_pk_mul_f32 v[10:11], v[10:11], v[24:25] op_sel_hi:[1,0]
	v_pk_mul_f32 v[8:9], v[8:9], v[24:25] op_sel_hi:[1,0]
	v_add_f32_e32 v27, 1.0, v27
	v_rcp_f32_e32 v27, v27
	v_mul_f32_e32 v24, v25, v28
	v_mul_f32_e32 v28, v12, v24
	v_lshlrev_b32_e32 v25, 16, v29
	v_lshlrev_b32_e32 v24, 16, v33
	v_mul_f32_e32 v12, v26, v27
	v_fma_f32 v26, v82, v44, v86
	v_pk_mul_f32 v[24:25], v[56:57], v[24:25]
	v_fma_f32 v32, v83, v45, v87
	v_add_f32_e32 v25, v25, v26
	v_add_f32_e32 v26, v24, v25
	v_mul_f32_e32 v24, 0xbfb8aa3b, v26
	v_exp_f32_e32 v27, v24
	v_and_b32_e32 v25, 0xffff0000, v29
	v_and_b32_e32 v24, 0xffff0000, v33
	v_pk_mul_f32 v[24:25], v[78:79], v[24:25]
	v_mul_f32_e32 v29, v13, v12
	v_add_f32_e32 v25, v25, v32
	v_add_f32_e32 v24, v24, v25
	v_mul_f32_e32 v25, 0xbfb8aa3b, v24
	v_exp_f32_e32 v25, v25
	v_add_f32_e32 v12, 1.0, v27
	v_rcp_f32_e32 v27, v12
	v_lshlrev_b32_e32 v13, 16, v30
	v_add_f32_e32 v12, 1.0, v25
	v_rcp_f32_e32 v25, v12
	v_lshlrev_b32_e32 v12, 16, v34
	v_fma_f32 v32, v68, v46, v72
	v_pk_mul_f32 v[12:13], v[58:59], v[12:13]
	v_mul_f32_e32 v24, v24, v25
	v_add_f32_e32 v13, v13, v32
	v_add_f32_e32 v32, v12, v13
	v_mul_f32_e32 v12, 0xbfb8aa3b, v32
	v_exp_f32_e32 v12, v12
	v_mul_f32_e32 v13, v26, v27
	v_mul_f32_e32 v14, v14, v13
	v_and_b32_e32 v13, 0xffff0000, v30
	v_add_f32_e32 v12, 1.0, v12
	v_rcp_f32_e32 v25, v12
	v_and_b32_e32 v12, 0xffff0000, v34
	v_fma_f32 v26, v69, v40, v73
	v_pk_mul_f32 v[12:13], v[64:65], v[12:13]
	v_mul_f32_e32 v15, v15, v24
	v_add_f32_e32 v13, v13, v26
	v_add_f32_e32 v26, v12, v13
	v_mul_f32_e32 v12, 0xbfb8aa3b, v26
	v_exp_f32_e32 v12, v12
	v_mul_f32_e32 v13, v32, v25
	v_mul_f32_e32 v24, v8, v13
	v_lshlrev_b32_e32 v13, 16, v31
	v_add_f32_e32 v8, 1.0, v12
	v_lshlrev_b32_e32 v12, 16, v35
	v_fma_f32 v25, v70, v47, v74
	v_pk_mul_f32 v[12:13], v[62:63], v[12:13]
	v_fma_f32 v30, v71, v48, v75
	v_add_f32_e32 v13, v13, v25
	v_add_f32_e32 v25, v12, v13
	v_mul_f32_e32 v12, 0xbfb8aa3b, v25
	v_exp_f32_e32 v27, v12
	v_and_b32_e32 v13, 0xffff0000, v31
	v_and_b32_e32 v12, 0xffff0000, v35
	v_pk_mul_f32 v[12:13], v[66:67], v[12:13]
	v_rcp_f32_e32 v8, v8
	v_add_f32_e32 v13, v13, v30
	v_add_f32_e32 v12, v12, v13
	v_mul_f32_e32 v13, 0xbfb8aa3b, v12
	v_exp_f32_e32 v13, v13
	v_mul_f32_e32 v8, v26, v8
	v_add_f32_e32 v26, 1.0, v27
	v_rcp_f32_e32 v26, v26
	v_add_f32_e32 v13, 1.0, v13
	v_rcp_f32_e32 v13, v13
	v_mul_f32_e32 v27, v9, v8
	v_mul_f32_e32 v8, v25, v26
	v_mul_f32_e32 v25, v10, v8
	v_mul_f32_e32 v8, v12, v13
	v_mul_f32_e32 v11, v11, v8
	v_cvt_pk_bf16_f32 v8, v28, v29
	v_cvt_pk_bf16_f32 v9, v14, v15
	v_cvt_pk_bf16_f32 v10, v24, v27
	v_cvt_pk_bf16_f32 v11, v25, v11
	global_store_dwordx4 v[124:125], v[8:11], off offset:256 nt
	s_waitcnt vmcnt(2)
	v_and_b32_e32 v12, 0xffff0000, v36
	v_fma_f32 v12, v81, v12, v85
	s_waitcnt vmcnt(1)
	v_fmamk_f32 v8, v41, 0x3a000000, v229
	v_rsq_f32_e32 v8, v8
	v_lshlrev_b32_e32 v9, 16, v36
	v_lshlrev_b32_e32 v11, 16, v20
	v_lshlrev_b32_e32 v10, 16, v16
	v_pk_mul_f32 v[6:7], v[6:7], v[8:9] op_sel_hi:[1,0]
	v_pk_mul_f32 v[4:5], v[4:5], v[8:9] op_sel_hi:[1,0]
	v_fma_f32 v9, v80, v9, v84
	v_pk_mul_f32 v[10:11], v[60:61], v[10:11]
	v_lshlrev_b32_e32 v13, 16, v37
	v_add_f32_e32 v9, v11, v9
	v_add_f32_e32 v9, v10, v9
	v_mul_f32_e32 v10, 0xbfb8aa3b, v9
	v_exp_f32_e32 v27, v10
	v_and_b32_e32 v11, 0xffff0000, v20
	v_and_b32_e32 v10, 0xffff0000, v16
	v_pk_mul_f32 v[10:11], v[76:77], v[10:11]
	v_pk_mul_f32 v[2:3], v[2:3], v[8:9] op_sel_hi:[1,0]
	v_add_f32_e32 v11, v11, v12
	v_add_f32_e32 v10, v10, v11
	v_mul_f32_e32 v11, 0xbfb8aa3b, v10
	v_exp_f32_e32 v11, v11
	v_add_f32_e32 v12, 1.0, v27
	v_rcp_f32_e32 v12, v12
	v_pk_mul_f32 v[0:1], v[0:1], v[8:9] op_sel_hi:[1,0]
	v_add_f32_e32 v11, 1.0, v11
	v_rcp_f32_e32 v11, v11
	v_mul_f32_e32 v8, v9, v12
	v_mul_f32_e32 v12, v4, v8
	v_lshlrev_b32_e32 v9, 16, v21
	v_lshlrev_b32_e32 v8, 16, v17
	v_mul_f32_e32 v4, v10, v11
	v_fma_f32 v10, v82, v13, v86
	v_pk_mul_f32 v[8:9], v[56:57], v[8:9]
	v_and_b32_e32 v14, 0xffff0000, v37
	v_add_f32_e32 v9, v9, v10
	v_add_f32_e32 v10, v8, v9
	v_mul_f32_e32 v8, 0xbfb8aa3b, v10
	v_exp_f32_e32 v11, v8
	v_and_b32_e32 v9, 0xffff0000, v21
	v_and_b32_e32 v8, 0xffff0000, v17
	v_fmac_f32_e32 v87, v83, v14
	v_pk_mul_f32 v[8:9], v[78:79], v[8:9]
	v_mul_f32_e32 v13, v5, v4
	v_add_f32_e32 v9, v9, v87
	v_add_f32_e32 v8, v8, v9
	v_mul_f32_e32 v9, 0xbfb8aa3b, v8
	v_exp_f32_e32 v9, v9
	v_add_f32_e32 v4, 1.0, v11
	v_rcp_f32_e32 v11, v4
	v_lshlrev_b32_e32 v15, 16, v38
	v_add_f32_e32 v4, 1.0, v9
	v_rcp_f32_e32 v9, v4
	v_lshlrev_b32_e32 v5, 16, v22
	v_lshlrev_b32_e32 v4, 16, v18
	v_fma_f32 v14, v68, v15, v72
	v_pk_mul_f32 v[4:5], v[58:59], v[4:5]
	v_and_b32_e32 v24, 0xffff0000, v38
	v_add_f32_e32 v5, v5, v14
	v_add_f32_e32 v14, v4, v5
	v_mul_f32_e32 v4, 0xbfb8aa3b, v14
	v_exp_f32_e32 v4, v4
	v_mul_f32_e32 v5, v10, v11
	v_mul_f32_e32 v6, v6, v5
	v_mul_f32_e32 v8, v8, v9
	v_add_f32_e32 v4, 1.0, v4
	v_rcp_f32_e32 v9, v4
	v_and_b32_e32 v5, 0xffff0000, v22
	v_and_b32_e32 v4, 0xffff0000, v18
	v_fma_f32 v10, v69, v24, v73
	v_pk_mul_f32 v[4:5], v[64:65], v[4:5]
	v_lshlrev_b32_e32 v25, 16, v39
	v_add_f32_e32 v5, v5, v10
	v_add_f32_e32 v10, v4, v5
	v_mul_f32_e32 v4, 0xbfb8aa3b, v10
	v_exp_f32_e32 v4, v4
	v_mul_f32_e32 v5, v14, v9
	v_mul_f32_e32 v7, v7, v8
	v_mul_f32_e32 v8, v0, v5
	v_add_f32_e32 v0, 1.0, v4
	v_lshlrev_b32_e32 v5, 16, v23
	v_lshlrev_b32_e32 v4, 16, v19
	v_fma_f32 v9, v70, v25, v74
	v_pk_mul_f32 v[4:5], v[62:63], v[4:5]
	v_and_b32_e32 v26, 0xffff0000, v39
	v_add_f32_e32 v5, v5, v9
	v_add_f32_e32 v9, v4, v5
	v_mul_f32_e32 v4, 0xbfb8aa3b, v9
	v_exp_f32_e32 v11, v4
	v_and_b32_e32 v5, 0xffff0000, v23
	v_and_b32_e32 v4, 0xffff0000, v19
	v_fmac_f32_e32 v75, v71, v26
	v_pk_mul_f32 v[4:5], v[66:67], v[4:5]
	v_rcp_f32_e32 v0, v0
	v_add_f32_e32 v5, v5, v75
	v_add_f32_e32 v4, v4, v5
	v_mul_f32_e32 v5, 0xbfb8aa3b, v4
	v_exp_f32_e32 v5, v5
	v_mul_f32_e32 v0, v10, v0
	v_add_f32_e32 v10, 1.0, v11
	v_rcp_f32_e32 v10, v10
	v_add_f32_e32 v5, 1.0, v5
	v_rcp_f32_e32 v5, v5
	v_mul_f32_e32 v11, v1, v0
	v_mul_f32_e32 v0, v9, v10
	v_mul_f32_e32 v9, v2, v0
	v_mul_f32_e32 v0, v4, v5
	v_mul_f32_e32 v3, v3, v0
	v_cvt_pk_bf16_f32 v0, v12, v13
	v_cvt_pk_bf16_f32 v1, v6, v7
	v_cvt_pk_bf16_f32 v2, v8, v11
	v_cvt_pk_bf16_f32 v3, v9, v3
	global_store_dwordx4 v[120:121], v[0:3], off offset:256 nt
	s_cbranch_vccnz .LBB0_999
	s_andn2_b64 vcc, exec, s[16:17]
	s_cbranch_vccnz .LBB0_998
	s_barrier
	s_branch .LBB0_998
